# v_m7 + scan loop: y reduction as reduce-scatter butterfly per 8 steps; DPP-chain gap slots filled with staging cvt/ds_write (steps 0-7) and butterfly ops (steps 8-15) instead of nops; no serial stagin
# baseline (speedup 1.0000x reference)
; DI void scan_item(const Params& p, int item, char* smem) {
;     ...
;   auto gload = [&](int ci) {
; #pragma unroll
;     for (int i = 0; i < 3; i++) {
;       int id = tid + i * 256;
;       int st = id / 48, rem = id % 48, vec = rem >> 3, part = rem & 7;
;       int t = tof(ci * 16 + st);
;       int vi = vec < 3 ? vec : vec + 3 * dir;
;       rg_[i] = *(const u32x4*)(SIb + ((long)t * 9 + vi) * 64 + part * 8);
;     }
;   };
;     ...
;   f32x2 Sa = {0.f, 0.f}, Sb = {0.f, 0.f};
;   __syncthreads();
;   gload(0);
;   lstore(0);
;   __syncthreads();
;   __builtin_amdgcn_s_setprio(3);
;   const int nch = T / 16;
;   const int voff = 128 + rg * 16 + rowl;
;   const int l16 = lane & 15;
;   struct StepIn { f32x4v r, k, w, d, b; float v; };
;   auto ldstep = [&](const float* b) {
;     StepIn x;
;     x.r = *(const f32x4v*)(b + cg4); x.k = *(const f32x4v*)(b + 64 + cg4); x.v = b[voff];
;     x.w = *(const f32x4v*)(b + 192 + cg4); x.d = *(const f32x4v*)(b + 256 + cg4); x.b = *(const f32x4v*)(b + 320 + cg4);
;     return x;
;   };
;   for (int ci = 0; ci < nch; ci++) {
;     if (ci + 1 < nch) gload(ci + 1);
;     const float* base = sIn + (ci & 1) * 16 * 6 * 64;
;     float ykeep = 0.f;
;     StepIn cur = ldstep(base);
; #pragma unroll
;     for (int st = 0; st < 16; st++) {
;       StepIn nxt = cur;
;       if (st + 1 < 16) nxt = ldstep(base + (st + 1) * 6 * 64);
;       __builtin_amdgcn_sched_barrier(0);
;       f32x2 ra = {cur.r.x, cur.r.y}, rb = {cur.r.z, cur.r.w}, ka = {cur.k.x, cur.k.y}, kb = {cur.k.z, cur.k.w};
;       f32x2 wa = {cur.w.x, cur.w.y}, wb = {cur.w.z, cur.w.w}, da = {cur.d.x, cur.d.y}, db = {cur.d.z, cur.d.w};
;       f32x2 ba = {cur.b.x, cur.b.y}, bb2 = {cur.b.z, cur.b.w};
;       f32x2 pp = Sa * ka + Sb * kb;
;       float sa = allreduce16(pp.x + pp.y);
;       f32x2 vv2 = {cur.v, cur.v};
;       f32x2 sa2 = {sa, sa};
;       Sa = (Sa * wa + vv2 * da) - sa2 * ba;
;       Sb = (Sb * wb + vv2 * db) - sa2 * bb2;
;       f32x2 yy = Sa * ra + Sb * rb;
;       float y = allreduce16(yy.x + yy.y);
;       ykeep = (l16 == st) ? y : ykeep;
;       cur = nxt;
;     }
.LBB0_398:
	v_lshlrev_b32_e32 v49, 2, v37
	v_lshlrev_b32_e32 v50, 2, v41
	v_and_b32_e32 v45, 1, v36
	v_cmp_ne_u32_e64 s[38:39], 0, v45
	v_and_b32_e32 v45, 2, v36
	v_cmp_ne_u32_e64 s[40:41], 0, v45
	v_and_b32_e32 v45, 4, v36
	v_cmp_ne_u32_e64 s[42:43], 0, v45
	v_and_b32_e32 v45, 8, v36
	v_cmp_ne_u32_e64 s[44:45], 0, v45
	v_mad_u32_u24 v32, v13, 6, v12
	v_mad_u32_u24 v33, v17, 6, v16
	v_mad_u32_u24 v34, v21, 6, v20
	v_lshl_or_b32 v32, v32, 8, v38
	v_lshl_or_b32 v33, v33, 8, v39
	v_lshl_or_b32 v34, v34, 8, v40
	s_movk_i32 s72, 0x10
	v_add_u32_e32 v0, s72, v13
	v_add_u32_e32 v4, s72, v17
	v_add_u32_e32 v8, s72, v21
	v_cmp_lt_i32_e32 vcc, 0xff, v0
	s_nop 1
	v_cndmask_b32_e32 v1, v208, v209, vcc
	v_cmp_lt_i32_e32 vcc, 0xff, v4
	v_sub_u32_e32 v1, v1, v0
	v_cndmask_b32_e64 v0, v1, v0, s[36:37]
	v_cndmask_b32_e32 v5, v208, v209, vcc
	v_cmp_lt_i32_e32 vcc, 0xff, v8
	v_sub_u32_e32 v5, v5, v4
	v_cndmask_b32_e64 v4, v5, v4, s[36:37]
	v_cndmask_b32_e32 v9, v208, v209, vcc
	v_sub_u32_e32 v9, v9, v8
	v_cndmask_b32_e64 v8, v9, v8, s[36:37]
	v_mad_i64_i32 v[0:1], s[12:13], v0, 9, v[14:15]
	v_mad_i64_i32 v[4:5], s[12:13], v4, 9, v[18:19]
	v_mad_i64_i32 v[8:9], s[12:13], v8, 9, v[22:23]
	v_lshlrev_b64 v[0:1], 7, v[0:1]
	v_lshlrev_b64 v[4:5], 7, v[4:5]
	v_lshlrev_b64 v[8:9], 7, v[8:9]
	v_lshl_add_u64 v[0:1], v[24:25], 0, v[0:1]
	v_lshl_add_u64 v[4:5], v[26:27], 0, v[4:5]
	v_lshl_add_u64 v[8:9], v[28:29], 0, v[8:9]
	v_mov_b64_e32 v[236:237], v[0:1]
	v_mov_b64_e32 v[238:239], v[4:5]
	v_mov_b64_e32 v[240:241], v[8:9]
	global_load_dwordx4 v[0:3], v[236:237], off
	global_load_dwordx4 v[4:7], v[238:239], off
	global_load_dwordx4 v[8:11], v[240:241], off
	v_sub_u32_e32 v243, 0xff, v36
	v_cndmask_b32_e64 v242, v243, v36, s[36:37]
	v_mov_b32_e32 v243, 0
	v_lshlrev_b64 v[242:243], 9, v[242:243]
	v_lshl_add_u64 v[242:243], v[30:31], 0, v[242:243]
	s_mov_b32 s26, 0
.Lscan_loop:
	ds_read_b128 v[72:75], v49 offset:256
	ds_read_b32 v88, v50 offset:512
	ds_read_b128 v[80:83], v49 offset:1024
	ds_read_b128 v[76:79], v49 offset:768
	ds_read_b128 v[84:87], v49 offset:1280
	ds_read_b128 v[68:71], v49
	ds_read_b128 v[100:103], v49 offset:1792
	ds_read_b32 v116, v50 offset:2048
	ds_read_b128 v[108:111], v49 offset:2560
	ds_read_b128 v[104:107], v49 offset:2304
	ds_read_b128 v[112:115], v49 offset:2816
	ds_read_b128 v[96:99], v49 offset:1536
	s_add_i32 s72, s26, 32
	s_mov_b32 vcc_hi, 0x4c3800
	s_cmp_eq_u32 s72, 0x100
	s_cselect_b32 vcc_lo, vcc_hi, 0xffffb800
	s_cmp_lg_u32 s36, 0
	s_cselect_b32 vcc_lo, 0x4800, vcc_lo
	s_cmp_ge_u32 s72, 0x1100
	s_cselect_b32 vcc_lo, 0, vcc_lo
	s_ashr_i32 vcc_hi, vcc_lo, 31
	v_lshl_add_u64 v[236:237], v[236:237], 0, vcc
	v_lshl_add_u64 v[238:239], v[238:239], 0, vcc
	v_lshl_add_u64 v[240:241], v[240:241], 0, vcc
	global_load_dwordx4 v[162:165], v[236:237], off
	global_load_dwordx4 v[166:169], v[238:239], off
	global_load_dwordx4 v[170:173], v[240:241], off
	s_waitcnt lgkmcnt(6)
	ds_read_b128 v[122:125], v49 offset:3328
	ds_read_b32 v138, v50 offset:3584
	ds_read_b128 v[130:133], v49 offset:4096
	ds_read_b128 v[126:129], v49 offset:3840
	ds_read_b128 v[134:137], v49 offset:4352
	ds_read_b128 v[118:121], v49 offset:3072
	v_pk_mul_f32 v[56:57], v[90:91], v[72:73]
	v_pk_mul_f32 v[60:61], v[88:89], v[80:81] op_sel_hi:[0,1]
	v_pk_fma_f32 v[56:57], v[92:93], v[74:75], v[56:57]
	v_pk_mul_f32 v[62:63], v[88:89], v[82:83] op_sel_hi:[0,1]
	v_add_f32_e32 v58, v56, v57
	v_pk_fma_f32 v[60:61], v[90:91], v[76:77], v[60:61]
	v_pk_fma_f32 v[62:63], v[92:93], v[78:79], v[62:63]
	v_add_f32_dpp v58, v58, v58 quad_perm:[1,0,3,2] row_mask:0xf bank_mask:0xf bound_ctrl:1
	s_waitcnt vmcnt(5)
	v_cvt_f32_f16_e32 v40, v0
	v_cvt_f32_f16_sdwa v41, v0 dst_sel:DWORD dst_unused:UNUSED_PAD src0_sel:WORD_1
	v_add_f32_dpp v58, v58, v58 quad_perm:[2,3,0,1] row_mask:0xf bank_mask:0xf bound_ctrl:1
	v_cvt_f32_f16_e32 v42, v1
	v_cvt_f32_f16_sdwa v43, v1 dst_sel:DWORD dst_unused:UNUSED_PAD src0_sel:WORD_1
	v_add_f32_dpp v58, v58, v58 row_half_mirror row_mask:0xf bank_mask:0xf bound_ctrl:1
	ds_write_b128 v32, v[40:43] offset:24576
	v_cvt_f32_f16_e32 v44, v2
	v_add_f32_dpp v58, v58, v58 row_mirror row_mask:0xf bank_mask:0xf bound_ctrl:1
	v_cvt_f32_f16_sdwa v45, v2 dst_sel:DWORD dst_unused:UNUSED_PAD src0_sel:WORD_1
	v_pk_fma_f32 v[90:91], v[84:85], v[58:59], v[60:61] op_sel_hi:[1,0,1] neg_lo:[1,0,0] neg_hi:[1,0,0]
	v_pk_fma_f32 v[92:93], v[86:87], v[58:59], v[62:63] op_sel_hi:[1,0,1] neg_lo:[1,0,0] neg_hi:[1,0,0]
	s_waitcnt lgkmcnt(7)
	ds_read_b128 v[144:147], v49 offset:4864
	ds_read_b32 v160, v50 offset:5120
	ds_read_b128 v[152:155], v49 offset:5632
	ds_read_b128 v[148:151], v49 offset:5376
	ds_read_b128 v[156:159], v49 offset:5888
	ds_read_b128 v[140:143], v49 offset:4608
	v_pk_mul_f32 v[56:57], v[90:91], v[100:101]
	v_pk_mul_f32 v[64:65], v[70:71], v[92:93]
	v_pk_fma_f32 v[56:57], v[92:93], v[102:103], v[56:57]
	v_pk_fma_f32 v[64:65], v[68:69], v[90:91], v[64:65]
	v_add_f32_e32 v58, v56, v57
	v_add_f32_e32 v244, v64, v65
	v_pk_mul_f32 v[60:61], v[116:117], v[108:109] op_sel_hi:[0,1]
	v_add_f32_dpp v58, v58, v58 quad_perm:[1,0,3,2] row_mask:0xf bank_mask:0xf bound_ctrl:1
	v_cvt_f32_f16_e32 v46, v3
	v_pk_fma_f32 v[60:61], v[90:91], v[104:105], v[60:61]
	v_add_f32_dpp v58, v58, v58 quad_perm:[2,3,0,1] row_mask:0xf bank_mask:0xf bound_ctrl:1
	v_cvt_f32_f16_sdwa v47, v3 dst_sel:DWORD dst_unused:UNUSED_PAD src0_sel:WORD_1
	v_pk_mul_f32 v[62:63], v[116:117], v[110:111] op_sel_hi:[0,1]
	v_add_f32_dpp v58, v58, v58 row_half_mirror row_mask:0xf bank_mask:0xf bound_ctrl:1
	ds_write_b128 v32, v[44:47] offset:24592
	v_pk_fma_f32 v[62:63], v[92:93], v[106:107], v[62:63]
	v_add_f32_dpp v58, v58, v58 row_mirror row_mask:0xf bank_mask:0xf bound_ctrl:1
	v_pk_fma_f32 v[90:91], v[112:113], v[58:59], v[60:61] op_sel_hi:[1,0,1] neg_lo:[1,0,0] neg_hi:[1,0,0]
	v_pk_fma_f32 v[92:93], v[114:115], v[58:59], v[62:63] op_sel_hi:[1,0,1] neg_lo:[1,0,0] neg_hi:[1,0,0]
	s_waitcnt lgkmcnt(8)
; DI void scan_item(const Params& p, int item, char* smem) {
;     ...
;   auto lstore = [&](int buf) {
; #pragma unroll
;     for (int i = 0; i < 3; i++) {
;       int id = tid + i * 256;
;       int st = id / 48, rem = id % 48, vec = rem >> 3, part = rem & 7;
;       h8 hv = __builtin_bit_cast(h8, rg_[i]);
;       f8 fv = __builtin_convertvector(hv, f8);
;       float* d = sIn + ((buf * 16 + st) * 6 + vec) * 64 + part * 8;
;       *(f32x4v*)d = f32x4v{fv[0], fv[1], fv[2], fv[3]};
;       *(f32x4v*)(d + 4) = f32x4v{fv[4], fv[5], fv[6], fv[7]};
;     }
;   };
;     ...
;     for (int st = 0; st < 16; st++) {
;       StepIn nxt = cur;
;       if (st + 1 < 16) nxt = ldstep(base + (st + 1) * 6 * 64);
;       __builtin_amdgcn_sched_barrier(0);
;       f32x2 ra = {cur.r.x, cur.r.y}, rb = {cur.r.z, cur.r.w}, ka = {cur.k.x, cur.k.y}, kb = {cur.k.z, cur.k.w};
;       f32x2 wa = {cur.w.x, cur.w.y}, wb = {cur.w.z, cur.w.w}, da = {cur.d.x, cur.d.y}, db = {cur.d.z, cur.d.w};
;       f32x2 ba = {cur.b.x, cur.b.y}, bb2 = {cur.b.z, cur.b.w};
;       f32x2 pp = Sa * ka + Sb * kb;
;       float sa = allreduce16(pp.x + pp.y);
;       f32x2 vv2 = {cur.v, cur.v};
;       f32x2 sa2 = {sa, sa};
;       Sa = (Sa * wa + vv2 * da) - sa2 * ba;
;       Sb = (Sb * wb + vv2 * db) - sa2 * bb2;
;       f32x2 yy = Sa * ra + Sb * rb;
;       float y = allreduce16(yy.x + yy.y);
;       ykeep = (l16 == st) ? y : ykeep;
;       cur = nxt;
;     }
	ds_read_b128 v[72:75], v49 offset:6400
	ds_read_b32 v88, v50 offset:6656
	ds_read_b128 v[80:83], v49 offset:7168
	ds_read_b128 v[76:79], v49 offset:6912
	ds_read_b128 v[84:87], v49 offset:7424
	ds_read_b128 v[68:71], v49 offset:6144
	v_pk_mul_f32 v[56:57], v[90:91], v[122:123]
	v_pk_mul_f32 v[64:65], v[98:99], v[92:93]
	v_pk_fma_f32 v[56:57], v[92:93], v[124:125], v[56:57]
	v_pk_fma_f32 v[64:65], v[96:97], v[90:91], v[64:65]
	v_add_f32_e32 v58, v56, v57
	v_add_f32_e32 v245, v64, v65
	v_pk_mul_f32 v[60:61], v[138:139], v[130:131] op_sel_hi:[0,1]
	v_add_f32_dpp v58, v58, v58 quad_perm:[1,0,3,2] row_mask:0xf bank_mask:0xf bound_ctrl:1
	s_waitcnt vmcnt(4)
	v_cvt_f32_f16_e32 v40, v4
	v_pk_fma_f32 v[60:61], v[90:91], v[126:127], v[60:61]
	v_add_f32_dpp v58, v58, v58 quad_perm:[2,3,0,1] row_mask:0xf bank_mask:0xf bound_ctrl:1
	v_cvt_f32_f16_sdwa v41, v4 dst_sel:DWORD dst_unused:UNUSED_PAD src0_sel:WORD_1
	v_pk_mul_f32 v[62:63], v[138:139], v[132:133] op_sel_hi:[0,1]
	v_add_f32_dpp v58, v58, v58 row_half_mirror row_mask:0xf bank_mask:0xf bound_ctrl:1
	v_cvt_f32_f16_e32 v42, v5
	v_pk_fma_f32 v[62:63], v[92:93], v[128:129], v[62:63]
	v_add_f32_dpp v58, v58, v58 row_mirror row_mask:0xf bank_mask:0xf bound_ctrl:1
	v_pk_fma_f32 v[90:91], v[134:135], v[58:59], v[60:61] op_sel_hi:[1,0,1] neg_lo:[1,0,0] neg_hi:[1,0,0]
	v_pk_fma_f32 v[92:93], v[136:137], v[58:59], v[62:63] op_sel_hi:[1,0,1] neg_lo:[1,0,0] neg_hi:[1,0,0]
	s_waitcnt lgkmcnt(7)
	ds_read_b128 v[100:103], v49 offset:7936
	ds_read_b32 v116, v50 offset:8192
	ds_read_b128 v[108:111], v49 offset:8704
	ds_read_b128 v[104:107], v49 offset:8448
	ds_read_b128 v[112:115], v49 offset:8960
	ds_read_b128 v[96:99], v49 offset:7680
	v_pk_mul_f32 v[56:57], v[90:91], v[144:145]
	v_pk_mul_f32 v[64:65], v[120:121], v[92:93]
	v_pk_fma_f32 v[56:57], v[92:93], v[146:147], v[56:57]
	v_pk_fma_f32 v[64:65], v[118:119], v[90:91], v[64:65]
	v_add_f32_e32 v58, v56, v57
	v_add_f32_e32 v246, v64, v65
	v_pk_mul_f32 v[60:61], v[160:161], v[152:153] op_sel_hi:[0,1]
	v_add_f32_dpp v58, v58, v58 quad_perm:[1,0,3,2] row_mask:0xf bank_mask:0xf bound_ctrl:1
	v_cvt_f32_f16_sdwa v43, v5 dst_sel:DWORD dst_unused:UNUSED_PAD src0_sel:WORD_1
	v_pk_fma_f32 v[60:61], v[90:91], v[148:149], v[60:61]
	v_add_f32_dpp v58, v58, v58 quad_perm:[2,3,0,1] row_mask:0xf bank_mask:0xf bound_ctrl:1
	ds_write_b128 v33, v[40:43] offset:24576
	v_pk_mul_f32 v[62:63], v[160:161], v[154:155] op_sel_hi:[0,1]
	v_add_f32_dpp v58, v58, v58 row_half_mirror row_mask:0xf bank_mask:0xf bound_ctrl:1
	v_cvt_f32_f16_e32 v44, v6
	v_pk_fma_f32 v[62:63], v[92:93], v[150:151], v[62:63]
	v_add_f32_dpp v58, v58, v58 row_mirror row_mask:0xf bank_mask:0xf bound_ctrl:1
	v_pk_fma_f32 v[90:91], v[156:157], v[58:59], v[60:61] op_sel_hi:[1,0,1] neg_lo:[1,0,0] neg_hi:[1,0,0]
	v_pk_fma_f32 v[92:93], v[158:159], v[58:59], v[62:63] op_sel_hi:[1,0,1] neg_lo:[1,0,0] neg_hi:[1,0,0]
	s_waitcnt lgkmcnt(7)
	ds_read_b128 v[122:125], v49 offset:9472
	ds_read_b32 v138, v50 offset:9728
	ds_read_b128 v[130:133], v49 offset:10240
	ds_read_b128 v[126:129], v49 offset:9984
	ds_read_b128 v[134:137], v49 offset:10496
	ds_read_b128 v[118:121], v49 offset:9216
	v_pk_mul_f32 v[56:57], v[90:91], v[72:73]
	v_pk_mul_f32 v[64:65], v[142:143], v[92:93]
	v_pk_fma_f32 v[56:57], v[92:93], v[74:75], v[56:57]
	v_pk_fma_f32 v[64:65], v[140:141], v[90:91], v[64:65]
	v_add_f32_e32 v58, v56, v57
	v_add_f32_e32 v247, v64, v65
	v_pk_mul_f32 v[60:61], v[88:89], v[80:81] op_sel_hi:[0,1]
	v_add_f32_dpp v58, v58, v58 quad_perm:[1,0,3,2] row_mask:0xf bank_mask:0xf bound_ctrl:1
	v_cvt_f32_f16_sdwa v45, v6 dst_sel:DWORD dst_unused:UNUSED_PAD src0_sel:WORD_1
	v_pk_fma_f32 v[60:61], v[90:91], v[76:77], v[60:61]
	v_add_f32_dpp v58, v58, v58 quad_perm:[2,3,0,1] row_mask:0xf bank_mask:0xf bound_ctrl:1
	v_cvt_f32_f16_e32 v46, v7
	v_pk_mul_f32 v[62:63], v[88:89], v[82:83] op_sel_hi:[0,1]
	v_add_f32_dpp v58, v58, v58 row_half_mirror row_mask:0xf bank_mask:0xf bound_ctrl:1
	v_cvt_f32_f16_sdwa v47, v7 dst_sel:DWORD dst_unused:UNUSED_PAD src0_sel:WORD_1
	v_pk_fma_f32 v[62:63], v[92:93], v[78:79], v[62:63]
	v_add_f32_dpp v58, v58, v58 row_mirror row_mask:0xf bank_mask:0xf bound_ctrl:1
	v_pk_fma_f32 v[90:91], v[84:85], v[58:59], v[60:61] op_sel_hi:[1,0,1] neg_lo:[1,0,0] neg_hi:[1,0,0]
	v_pk_fma_f32 v[92:93], v[86:87], v[58:59], v[62:63] op_sel_hi:[1,0,1] neg_lo:[1,0,0] neg_hi:[1,0,0]
	s_waitcnt lgkmcnt(7)
	ds_read_b128 v[144:147], v49 offset:11008
	ds_read_b32 v160, v50 offset:11264
	ds_read_b128 v[152:155], v49 offset:11776
	ds_read_b128 v[148:151], v49 offset:11520
	ds_read_b128 v[156:159], v49 offset:12032
	ds_read_b128 v[140:143], v49 offset:10752
	v_pk_mul_f32 v[56:57], v[90:91], v[100:101]
	v_pk_mul_f32 v[64:65], v[70:71], v[92:93]
	v_pk_fma_f32 v[56:57], v[92:93], v[102:103], v[56:57]
	v_pk_fma_f32 v[64:65], v[68:69], v[90:91], v[64:65]
	v_add_f32_e32 v58, v56, v57
	v_add_f32_e32 v248, v64, v65
	v_pk_mul_f32 v[60:61], v[116:117], v[108:109] op_sel_hi:[0,1]
	v_add_f32_dpp v58, v58, v58 quad_perm:[1,0,3,2] row_mask:0xf bank_mask:0xf bound_ctrl:1
	ds_write_b128 v33, v[44:47] offset:24592
	v_pk_fma_f32 v[60:61], v[90:91], v[104:105], v[60:61]
	v_add_f32_dpp v58, v58, v58 quad_perm:[2,3,0,1] row_mask:0xf bank_mask:0xf bound_ctrl:1
	s_waitcnt vmcnt(3)
	v_cvt_f32_f16_e32 v40, v8
	v_pk_mul_f32 v[62:63], v[116:117], v[110:111] op_sel_hi:[0,1]
	v_add_f32_dpp v58, v58, v58 row_half_mirror row_mask:0xf bank_mask:0xf bound_ctrl:1
	v_cvt_f32_f16_sdwa v41, v8 dst_sel:DWORD dst_unused:UNUSED_PAD src0_sel:WORD_1
	v_pk_fma_f32 v[62:63], v[92:93], v[106:107], v[62:63]
	v_add_f32_dpp v58, v58, v58 row_mirror row_mask:0xf bank_mask:0xf bound_ctrl:1
	v_pk_fma_f32 v[90:91], v[112:113], v[58:59], v[60:61] op_sel_hi:[1,0,1] neg_lo:[1,0,0] neg_hi:[1,0,0]
	v_pk_fma_f32 v[92:93], v[114:115], v[58:59], v[62:63] op_sel_hi:[1,0,1] neg_lo:[1,0,0] neg_hi:[1,0,0]
	s_waitcnt lgkmcnt(7)
; DI void scan_item(const Params& p, int item, char* smem) {
;     ...
;   auto lstore = [&](int buf) {
; #pragma unroll
;     for (int i = 0; i < 3; i++) {
;       int id = tid + i * 256;
;       int st = id / 48, rem = id % 48, vec = rem >> 3, part = rem & 7;
;       h8 hv = __builtin_bit_cast(h8, rg_[i]);
;       f8 fv = __builtin_convertvector(hv, f8);
;       float* d = sIn + ((buf * 16 + st) * 6 + vec) * 64 + part * 8;
;       *(f32x4v*)d = f32x4v{fv[0], fv[1], fv[2], fv[3]};
;       *(f32x4v*)(d + 4) = f32x4v{fv[4], fv[5], fv[6], fv[7]};
;     }
;   };
;     ...
;     for (int st = 0; st < 16; st++) {
;       StepIn nxt = cur;
;       if (st + 1 < 16) nxt = ldstep(base + (st + 1) * 6 * 64);
;       __builtin_amdgcn_sched_barrier(0);
;       f32x2 ra = {cur.r.x, cur.r.y}, rb = {cur.r.z, cur.r.w}, ka = {cur.k.x, cur.k.y}, kb = {cur.k.z, cur.k.w};
;       f32x2 wa = {cur.w.x, cur.w.y}, wb = {cur.w.z, cur.w.w}, da = {cur.d.x, cur.d.y}, db = {cur.d.z, cur.d.w};
;       f32x2 ba = {cur.b.x, cur.b.y}, bb2 = {cur.b.z, cur.b.w};
;       f32x2 pp = Sa * ka + Sb * kb;
;       float sa = allreduce16(pp.x + pp.y);
;       f32x2 vv2 = {cur.v, cur.v};
;       f32x2 sa2 = {sa, sa};
;       Sa = (Sa * wa + vv2 * da) - sa2 * ba;
;       Sb = (Sb * wb + vv2 * db) - sa2 * bb2;
;       f32x2 yy = Sa * ra + Sb * rb;
;       float y = allreduce16(yy.x + yy.y);
;       ykeep = (l16 == st) ? y : ykeep;
;       cur = nxt;
;     }
	ds_read_b128 v[72:75], v49 offset:12544
	ds_read_b32 v88, v50 offset:12800
	ds_read_b128 v[80:83], v49 offset:13312
	ds_read_b128 v[76:79], v49 offset:13056
	ds_read_b128 v[84:87], v49 offset:13568
	ds_read_b128 v[68:71], v49 offset:12288
	v_pk_mul_f32 v[56:57], v[90:91], v[122:123]
	v_pk_mul_f32 v[64:65], v[98:99], v[92:93]
	v_pk_fma_f32 v[56:57], v[92:93], v[124:125], v[56:57]
	v_pk_fma_f32 v[64:65], v[96:97], v[90:91], v[64:65]
	v_add_f32_e32 v58, v56, v57
	v_add_f32_e32 v249, v64, v65
	v_pk_mul_f32 v[60:61], v[138:139], v[130:131] op_sel_hi:[0,1]
	v_add_f32_dpp v58, v58, v58 quad_perm:[1,0,3,2] row_mask:0xf bank_mask:0xf bound_ctrl:1
	v_cvt_f32_f16_e32 v42, v9
	v_pk_fma_f32 v[60:61], v[90:91], v[126:127], v[60:61]
	v_add_f32_dpp v58, v58, v58 quad_perm:[2,3,0,1] row_mask:0xf bank_mask:0xf bound_ctrl:1
	v_cvt_f32_f16_sdwa v43, v9 dst_sel:DWORD dst_unused:UNUSED_PAD src0_sel:WORD_1
	v_pk_mul_f32 v[62:63], v[138:139], v[132:133] op_sel_hi:[0,1]
	v_add_f32_dpp v58, v58, v58 row_half_mirror row_mask:0xf bank_mask:0xf bound_ctrl:1
	ds_write_b128 v34, v[40:43] offset:24576
	v_pk_fma_f32 v[62:63], v[92:93], v[128:129], v[62:63]
	v_add_f32_dpp v58, v58, v58 row_mirror row_mask:0xf bank_mask:0xf bound_ctrl:1
	v_pk_fma_f32 v[90:91], v[134:135], v[58:59], v[60:61] op_sel_hi:[1,0,1] neg_lo:[1,0,0] neg_hi:[1,0,0]
	v_pk_fma_f32 v[92:93], v[136:137], v[58:59], v[62:63] op_sel_hi:[1,0,1] neg_lo:[1,0,0] neg_hi:[1,0,0]
	s_waitcnt lgkmcnt(8)
	ds_read_b128 v[100:103], v49 offset:14080
	ds_read_b32 v116, v50 offset:14336
	ds_read_b128 v[108:111], v49 offset:14848
	ds_read_b128 v[104:107], v49 offset:14592
	ds_read_b128 v[112:115], v49 offset:15104
	ds_read_b128 v[96:99], v49 offset:13824
	v_pk_mul_f32 v[56:57], v[90:91], v[144:145]
	v_pk_mul_f32 v[64:65], v[120:121], v[92:93]
	v_pk_fma_f32 v[56:57], v[92:93], v[146:147], v[56:57]
	v_pk_fma_f32 v[64:65], v[118:119], v[90:91], v[64:65]
	v_add_f32_e32 v58, v56, v57
	v_add_f32_e32 v250, v64, v65
	v_pk_mul_f32 v[60:61], v[160:161], v[152:153] op_sel_hi:[0,1]
	v_add_f32_dpp v58, v58, v58 quad_perm:[1,0,3,2] row_mask:0xf bank_mask:0xf bound_ctrl:1
	v_cvt_f32_f16_e32 v44, v10
	v_pk_fma_f32 v[60:61], v[90:91], v[148:149], v[60:61]
	v_add_f32_dpp v58, v58, v58 quad_perm:[2,3,0,1] row_mask:0xf bank_mask:0xf bound_ctrl:1
	v_cvt_f32_f16_sdwa v45, v10 dst_sel:DWORD dst_unused:UNUSED_PAD src0_sel:WORD_1
	v_pk_mul_f32 v[62:63], v[160:161], v[154:155] op_sel_hi:[0,1]
	v_add_f32_dpp v58, v58, v58 row_half_mirror row_mask:0xf bank_mask:0xf bound_ctrl:1
	v_cvt_f32_f16_e32 v46, v11
	v_pk_fma_f32 v[62:63], v[92:93], v[150:151], v[62:63]
	v_add_f32_dpp v58, v58, v58 row_mirror row_mask:0xf bank_mask:0xf bound_ctrl:1
	v_pk_fma_f32 v[90:91], v[156:157], v[58:59], v[60:61] op_sel_hi:[1,0,1] neg_lo:[1,0,0] neg_hi:[1,0,0]
	v_pk_fma_f32 v[92:93], v[158:159], v[58:59], v[62:63] op_sel_hi:[1,0,1] neg_lo:[1,0,0] neg_hi:[1,0,0]
	v_cvt_f32_f16_sdwa v47, v11 dst_sel:DWORD dst_unused:UNUSED_PAD src0_sel:WORD_1
	ds_write_b128 v34, v[44:47] offset:24592
	s_waitcnt lgkmcnt(8)
	ds_read_b128 v[122:125], v49 offset:15616
	ds_read_b32 v138, v50 offset:15872
	ds_read_b128 v[130:133], v49 offset:16384
	ds_read_b128 v[126:129], v49 offset:16128
	ds_read_b128 v[134:137], v49 offset:16640
	ds_read_b128 v[118:121], v49 offset:15360
	v_pk_mul_f32 v[56:57], v[90:91], v[72:73]
	v_pk_mul_f32 v[64:65], v[142:143], v[92:93]
	v_pk_fma_f32 v[56:57], v[92:93], v[74:75], v[56:57]
	v_pk_fma_f32 v[64:65], v[140:141], v[90:91], v[64:65]
	v_add_f32_e32 v58, v56, v57
	v_add_f32_e32 v251, v64, v65
	v_pk_mul_f32 v[60:61], v[88:89], v[80:81] op_sel_hi:[0,1]
	v_add_f32_dpp v58, v58, v58 quad_perm:[1,0,3,2] row_mask:0xf bank_mask:0xf bound_ctrl:1
	v_add_f32_dpp v244, v244, v244 row_mirror row_mask:0xf bank_mask:0xf bound_ctrl:1
	v_pk_fma_f32 v[60:61], v[90:91], v[76:77], v[60:61]
	v_add_f32_dpp v58, v58, v58 quad_perm:[2,3,0,1] row_mask:0xf bank_mask:0xf bound_ctrl:1
	v_add_f32_dpp v245, v245, v245 row_mirror row_mask:0xf bank_mask:0xf bound_ctrl:1
	v_pk_mul_f32 v[62:63], v[88:89], v[82:83] op_sel_hi:[0,1]
	v_add_f32_dpp v58, v58, v58 row_half_mirror row_mask:0xf bank_mask:0xf bound_ctrl:1
	v_add_f32_dpp v246, v246, v246 row_mirror row_mask:0xf bank_mask:0xf bound_ctrl:1
	v_pk_fma_f32 v[62:63], v[92:93], v[78:79], v[62:63]
	v_add_f32_dpp v58, v58, v58 row_mirror row_mask:0xf bank_mask:0xf bound_ctrl:1
	v_pk_fma_f32 v[90:91], v[84:85], v[58:59], v[60:61] op_sel_hi:[1,0,1] neg_lo:[1,0,0] neg_hi:[1,0,0]
	v_pk_fma_f32 v[92:93], v[86:87], v[58:59], v[62:63] op_sel_hi:[1,0,1] neg_lo:[1,0,0] neg_hi:[1,0,0]
	s_waitcnt lgkmcnt(7)
	ds_read_b128 v[144:147], v49 offset:17152
	ds_read_b32 v160, v50 offset:17408
	ds_read_b128 v[152:155], v49 offset:17920
	ds_read_b128 v[148:151], v49 offset:17664
	ds_read_b128 v[156:159], v49 offset:18176
	ds_read_b128 v[140:143], v49 offset:16896
	v_pk_mul_f32 v[56:57], v[90:91], v[100:101]
	v_pk_mul_f32 v[64:65], v[70:71], v[92:93]
	v_pk_fma_f32 v[56:57], v[92:93], v[102:103], v[56:57]
	v_pk_fma_f32 v[64:65], v[68:69], v[90:91], v[64:65]
	v_add_f32_e32 v58, v56, v57
	v_add_f32_e32 v0, v64, v65
	v_pk_mul_f32 v[60:61], v[116:117], v[108:109] op_sel_hi:[0,1]
	v_add_f32_dpp v58, v58, v58 quad_perm:[1,0,3,2] row_mask:0xf bank_mask:0xf bound_ctrl:1
	v_add_f32_dpp v247, v247, v247 row_mirror row_mask:0xf bank_mask:0xf bound_ctrl:1
	v_pk_fma_f32 v[60:61], v[90:91], v[104:105], v[60:61]
	v_add_f32_dpp v58, v58, v58 quad_perm:[2,3,0,1] row_mask:0xf bank_mask:0xf bound_ctrl:1
	v_add_f32_dpp v248, v248, v248 row_mirror row_mask:0xf bank_mask:0xf bound_ctrl:1
	v_pk_mul_f32 v[62:63], v[116:117], v[110:111] op_sel_hi:[0,1]
	v_add_f32_dpp v58, v58, v58 row_half_mirror row_mask:0xf bank_mask:0xf bound_ctrl:1
	v_add_f32_dpp v249, v249, v249 row_mirror row_mask:0xf bank_mask:0xf bound_ctrl:1
	v_pk_fma_f32 v[62:63], v[92:93], v[106:107], v[62:63]
	v_add_f32_dpp v58, v58, v58 row_mirror row_mask:0xf bank_mask:0xf bound_ctrl:1
	v_pk_fma_f32 v[90:91], v[112:113], v[58:59], v[60:61] op_sel_hi:[1,0,1] neg_lo:[1,0,0] neg_hi:[1,0,0]
	v_pk_fma_f32 v[92:93], v[114:115], v[58:59], v[62:63] op_sel_hi:[1,0,1] neg_lo:[1,0,0] neg_hi:[1,0,0]
	s_waitcnt lgkmcnt(6)
; DI void scan_item(const Params& p, int item, char* smem) {
;     ...
;     for (int st = 0; st < 16; st++) {
;       StepIn nxt = cur;
;       if (st + 1 < 16) nxt = ldstep(base + (st + 1) * 6 * 64);
;       __builtin_amdgcn_sched_barrier(0);
;       f32x2 ra = {cur.r.x, cur.r.y}, rb = {cur.r.z, cur.r.w}, ka = {cur.k.x, cur.k.y}, kb = {cur.k.z, cur.k.w};
;       f32x2 wa = {cur.w.x, cur.w.y}, wb = {cur.w.z, cur.w.w}, da = {cur.d.x, cur.d.y}, db = {cur.d.z, cur.d.w};
;       f32x2 ba = {cur.b.x, cur.b.y}, bb2 = {cur.b.z, cur.b.w};
;       f32x2 pp = Sa * ka + Sb * kb;
;       float sa = allreduce16(pp.x + pp.y);
;       f32x2 vv2 = {cur.v, cur.v};
;       f32x2 sa2 = {sa, sa};
;       Sa = (Sa * wa + vv2 * da) - sa2 * ba;
;       Sb = (Sb * wb + vv2 * db) - sa2 * bb2;
;       f32x2 yy = Sa * ra + Sb * rb;
;       float y = allreduce16(yy.x + yy.y);
;       ykeep = (l16 == st) ? y : ykeep;
;       cur = nxt;
;     }
	ds_read_b128 v[72:75], v49 offset:18688
	ds_read_b32 v88, v50 offset:18944
	ds_read_b128 v[80:83], v49 offset:19456
	ds_read_b128 v[76:79], v49 offset:19200
	ds_read_b128 v[84:87], v49 offset:19712
	ds_read_b128 v[68:71], v49 offset:18432
	v_pk_mul_f32 v[56:57], v[90:91], v[122:123]
	v_pk_mul_f32 v[64:65], v[98:99], v[92:93]
	v_pk_fma_f32 v[56:57], v[92:93], v[124:125], v[56:57]
	v_pk_fma_f32 v[64:65], v[96:97], v[90:91], v[64:65]
	v_add_f32_e32 v58, v56, v57
	v_add_f32_e32 v1, v64, v65
	v_pk_mul_f32 v[60:61], v[138:139], v[130:131] op_sel_hi:[0,1]
	v_add_f32_dpp v58, v58, v58 quad_perm:[1,0,3,2] row_mask:0xf bank_mask:0xf bound_ctrl:1
	v_add_f32_dpp v250, v250, v250 row_mirror row_mask:0xf bank_mask:0xf bound_ctrl:1
	v_pk_fma_f32 v[60:61], v[90:91], v[126:127], v[60:61]
	v_add_f32_dpp v58, v58, v58 quad_perm:[2,3,0,1] row_mask:0xf bank_mask:0xf bound_ctrl:1
	v_add_f32_dpp v251, v251, v251 row_mirror row_mask:0xf bank_mask:0xf bound_ctrl:1
	v_pk_mul_f32 v[62:63], v[138:139], v[132:133] op_sel_hi:[0,1]
	v_add_f32_dpp v58, v58, v58 row_half_mirror row_mask:0xf bank_mask:0xf bound_ctrl:1
	v_add_f32_dpp v40, v244, v244 row_half_mirror row_mask:0xf bank_mask:0xf bound_ctrl:1
	v_pk_fma_f32 v[62:63], v[92:93], v[128:129], v[62:63]
	v_add_f32_dpp v58, v58, v58 row_mirror row_mask:0xf bank_mask:0xf bound_ctrl:1
	v_pk_fma_f32 v[90:91], v[134:135], v[58:59], v[60:61] op_sel_hi:[1,0,1] neg_lo:[1,0,0] neg_hi:[1,0,0]
	v_pk_fma_f32 v[92:93], v[136:137], v[58:59], v[62:63] op_sel_hi:[1,0,1] neg_lo:[1,0,0] neg_hi:[1,0,0]
	s_waitcnt lgkmcnt(6)
	ds_read_b128 v[100:103], v49 offset:20224
	ds_read_b32 v116, v50 offset:20480
	ds_read_b128 v[108:111], v49 offset:20992
	ds_read_b128 v[104:107], v49 offset:20736
	ds_read_b128 v[112:115], v49 offset:21248
	ds_read_b128 v[96:99], v49 offset:19968
	v_pk_mul_f32 v[56:57], v[90:91], v[144:145]
	v_pk_mul_f32 v[64:65], v[120:121], v[92:93]
	v_pk_fma_f32 v[56:57], v[92:93], v[146:147], v[56:57]
	v_pk_fma_f32 v[64:65], v[118:119], v[90:91], v[64:65]
	v_add_f32_e32 v58, v56, v57
	v_add_f32_e32 v2, v64, v65
	v_pk_mul_f32 v[60:61], v[160:161], v[152:153] op_sel_hi:[0,1]
	v_add_f32_dpp v58, v58, v58 quad_perm:[1,0,3,2] row_mask:0xf bank_mask:0xf bound_ctrl:1
	v_add_f32_dpp v41, v248, v248 row_half_mirror row_mask:0xf bank_mask:0xf bound_ctrl:1
	v_pk_fma_f32 v[60:61], v[90:91], v[148:149], v[60:61]
	v_add_f32_dpp v58, v58, v58 quad_perm:[2,3,0,1] row_mask:0xf bank_mask:0xf bound_ctrl:1
	v_cndmask_b32_e64 v244, v40, v41, s[42:43]
	v_pk_mul_f32 v[62:63], v[160:161], v[154:155] op_sel_hi:[0,1]
	v_add_f32_dpp v58, v58, v58 row_half_mirror row_mask:0xf bank_mask:0xf bound_ctrl:1
	v_add_f32_dpp v40, v245, v245 row_half_mirror row_mask:0xf bank_mask:0xf bound_ctrl:1
	v_pk_fma_f32 v[62:63], v[92:93], v[150:151], v[62:63]
	v_add_f32_dpp v58, v58, v58 row_mirror row_mask:0xf bank_mask:0xf bound_ctrl:1
	v_pk_fma_f32 v[90:91], v[156:157], v[58:59], v[60:61] op_sel_hi:[1,0,1] neg_lo:[1,0,0] neg_hi:[1,0,0]
	v_pk_fma_f32 v[92:93], v[158:159], v[58:59], v[62:63] op_sel_hi:[1,0,1] neg_lo:[1,0,0] neg_hi:[1,0,0]
	s_waitcnt lgkmcnt(6)
	ds_read_b128 v[122:125], v49 offset:21760
	ds_read_b32 v138, v50 offset:22016
	ds_read_b128 v[130:133], v49 offset:22528
	ds_read_b128 v[126:129], v49 offset:22272
	ds_read_b128 v[134:137], v49 offset:22784
	ds_read_b128 v[118:121], v49 offset:21504
	v_pk_mul_f32 v[56:57], v[90:91], v[72:73]
	v_pk_mul_f32 v[64:65], v[142:143], v[92:93]
	v_pk_fma_f32 v[56:57], v[92:93], v[74:75], v[56:57]
	v_pk_fma_f32 v[64:65], v[140:141], v[90:91], v[64:65]
	v_add_f32_e32 v58, v56, v57
	v_add_f32_e32 v3, v64, v65
	v_pk_mul_f32 v[60:61], v[88:89], v[80:81] op_sel_hi:[0,1]
	v_add_f32_dpp v58, v58, v58 quad_perm:[1,0,3,2] row_mask:0xf bank_mask:0xf bound_ctrl:1
	v_add_f32_dpp v41, v249, v249 row_half_mirror row_mask:0xf bank_mask:0xf bound_ctrl:1
	v_pk_fma_f32 v[60:61], v[90:91], v[76:77], v[60:61]
	v_add_f32_dpp v58, v58, v58 quad_perm:[2,3,0,1] row_mask:0xf bank_mask:0xf bound_ctrl:1
	v_cndmask_b32_e64 v245, v40, v41, s[42:43]
	v_pk_mul_f32 v[62:63], v[88:89], v[82:83] op_sel_hi:[0,1]
	v_add_f32_dpp v58, v58, v58 row_half_mirror row_mask:0xf bank_mask:0xf bound_ctrl:1
	v_add_f32_dpp v40, v246, v246 row_half_mirror row_mask:0xf bank_mask:0xf bound_ctrl:1
	v_pk_fma_f32 v[62:63], v[92:93], v[78:79], v[62:63]
	v_add_f32_dpp v58, v58, v58 row_mirror row_mask:0xf bank_mask:0xf bound_ctrl:1
	v_pk_fma_f32 v[90:91], v[84:85], v[58:59], v[60:61] op_sel_hi:[1,0,1] neg_lo:[1,0,0] neg_hi:[1,0,0]
	v_pk_fma_f32 v[92:93], v[86:87], v[58:59], v[62:63] op_sel_hi:[1,0,1] neg_lo:[1,0,0] neg_hi:[1,0,0]
	s_waitcnt lgkmcnt(6)
	ds_read_b128 v[144:147], v49 offset:23296
	ds_read_b32 v160, v50 offset:23552
	ds_read_b128 v[152:155], v49 offset:24064
	ds_read_b128 v[148:151], v49 offset:23808
	ds_read_b128 v[156:159], v49 offset:24320
	ds_read_b128 v[140:143], v49 offset:23040
	v_pk_mul_f32 v[56:57], v[90:91], v[100:101]
	v_pk_mul_f32 v[64:65], v[70:71], v[92:93]
	v_pk_fma_f32 v[56:57], v[92:93], v[102:103], v[56:57]
	v_pk_fma_f32 v[64:65], v[68:69], v[90:91], v[64:65]
	v_add_f32_e32 v58, v56, v57
	v_add_f32_e32 v4, v64, v65
	v_pk_mul_f32 v[60:61], v[116:117], v[108:109] op_sel_hi:[0,1]
	v_add_f32_dpp v58, v58, v58 quad_perm:[1,0,3,2] row_mask:0xf bank_mask:0xf bound_ctrl:1
	v_add_f32_dpp v41, v250, v250 row_half_mirror row_mask:0xf bank_mask:0xf bound_ctrl:1
	v_pk_fma_f32 v[60:61], v[90:91], v[104:105], v[60:61]
	v_add_f32_dpp v58, v58, v58 quad_perm:[2,3,0,1] row_mask:0xf bank_mask:0xf bound_ctrl:1
	v_cndmask_b32_e64 v246, v40, v41, s[42:43]
	v_pk_mul_f32 v[62:63], v[116:117], v[110:111] op_sel_hi:[0,1]
	v_add_f32_dpp v58, v58, v58 row_half_mirror row_mask:0xf bank_mask:0xf bound_ctrl:1
	v_add_f32_dpp v40, v247, v247 row_half_mirror row_mask:0xf bank_mask:0xf bound_ctrl:1
	v_pk_fma_f32 v[62:63], v[92:93], v[106:107], v[62:63]
	v_add_f32_dpp v58, v58, v58 row_mirror row_mask:0xf bank_mask:0xf bound_ctrl:1
	v_pk_fma_f32 v[90:91], v[112:113], v[58:59], v[60:61] op_sel_hi:[1,0,1] neg_lo:[1,0,0] neg_hi:[1,0,0]
	v_pk_fma_f32 v[92:93], v[114:115], v[58:59], v[62:63] op_sel_hi:[1,0,1] neg_lo:[1,0,0] neg_hi:[1,0,0]
	s_waitcnt lgkmcnt(6)
; DI void scan_item(const Params& p, int item, char* smem) {
;     ...
;     for (int st = 0; st < 16; st++) {
;       StepIn nxt = cur;
;       if (st + 1 < 16) nxt = ldstep(base + (st + 1) * 6 * 64);
;       __builtin_amdgcn_sched_barrier(0);
;       f32x2 ra = {cur.r.x, cur.r.y}, rb = {cur.r.z, cur.r.w}, ka = {cur.k.x, cur.k.y}, kb = {cur.k.z, cur.k.w};
;       f32x2 wa = {cur.w.x, cur.w.y}, wb = {cur.w.z, cur.w.w}, da = {cur.d.x, cur.d.y}, db = {cur.d.z, cur.d.w};
;       f32x2 ba = {cur.b.x, cur.b.y}, bb2 = {cur.b.z, cur.b.w};
;       f32x2 pp = Sa * ka + Sb * kb;
;       float sa = allreduce16(pp.x + pp.y);
;       f32x2 vv2 = {cur.v, cur.v};
;       f32x2 sa2 = {sa, sa};
;       Sa = (Sa * wa + vv2 * da) - sa2 * ba;
;       Sb = (Sb * wb + vv2 * db) - sa2 * bb2;
;       f32x2 yy = Sa * ra + Sb * rb;
;       float y = allreduce16(yy.x + yy.y);
;       ykeep = (l16 == st) ? y : ykeep;
;       cur = nxt;
;     }
;     { _Float16 yh = (_Float16)ykeep; yb[(long)tof(ci * 16 + l16) * 256 + rowl] = __builtin_bit_cast(u16, yh); }
;     if (ci + 1 < nch) lstore((ci + 1) & 1);
;     __syncthreads();
;   }
	v_pk_mul_f32 v[56:57], v[90:91], v[122:123]
	v_pk_mul_f32 v[64:65], v[98:99], v[92:93]
	v_pk_fma_f32 v[56:57], v[92:93], v[124:125], v[56:57]
	v_pk_fma_f32 v[64:65], v[96:97], v[90:91], v[64:65]
	v_add_f32_e32 v58, v56, v57
	v_add_f32_e32 v5, v64, v65
	v_pk_mul_f32 v[60:61], v[138:139], v[130:131] op_sel_hi:[0,1]
	v_add_f32_dpp v58, v58, v58 quad_perm:[1,0,3,2] row_mask:0xf bank_mask:0xf bound_ctrl:1
	v_add_f32_dpp v41, v251, v251 row_half_mirror row_mask:0xf bank_mask:0xf bound_ctrl:1
	v_pk_fma_f32 v[60:61], v[90:91], v[126:127], v[60:61]
	v_add_f32_dpp v58, v58, v58 quad_perm:[2,3,0,1] row_mask:0xf bank_mask:0xf bound_ctrl:1
	v_cndmask_b32_e64 v247, v40, v41, s[42:43]
	v_pk_mul_f32 v[62:63], v[138:139], v[132:133] op_sel_hi:[0,1]
	v_add_f32_dpp v58, v58, v58 row_half_mirror row_mask:0xf bank_mask:0xf bound_ctrl:1
	v_add_f32_dpp v40, v244, v244 quad_perm:[2,3,0,1] row_mask:0xf bank_mask:0xf bound_ctrl:1
	v_pk_fma_f32 v[62:63], v[92:93], v[128:129], v[62:63]
	v_add_f32_dpp v58, v58, v58 row_mirror row_mask:0xf bank_mask:0xf bound_ctrl:1
	v_pk_fma_f32 v[90:91], v[134:135], v[58:59], v[60:61] op_sel_hi:[1,0,1] neg_lo:[1,0,0] neg_hi:[1,0,0]
	v_pk_fma_f32 v[92:93], v[136:137], v[58:59], v[62:63] op_sel_hi:[1,0,1] neg_lo:[1,0,0] neg_hi:[1,0,0]
	s_waitcnt lgkmcnt(0)
	v_pk_mul_f32 v[56:57], v[90:91], v[144:145]
	v_pk_mul_f32 v[64:65], v[120:121], v[92:93]
	v_pk_fma_f32 v[56:57], v[92:93], v[146:147], v[56:57]
	v_pk_fma_f32 v[64:65], v[118:119], v[90:91], v[64:65]
	v_add_f32_e32 v58, v56, v57
	v_add_f32_e32 v6, v64, v65
	v_pk_mul_f32 v[60:61], v[160:161], v[152:153] op_sel_hi:[0,1]
	v_add_f32_dpp v58, v58, v58 quad_perm:[1,0,3,2] row_mask:0xf bank_mask:0xf bound_ctrl:1
	v_add_f32_dpp v41, v246, v246 quad_perm:[2,3,0,1] row_mask:0xf bank_mask:0xf bound_ctrl:1
	v_pk_fma_f32 v[60:61], v[90:91], v[148:149], v[60:61]
	v_add_f32_dpp v58, v58, v58 quad_perm:[2,3,0,1] row_mask:0xf bank_mask:0xf bound_ctrl:1
	v_cndmask_b32_e64 v244, v40, v41, s[40:41]
	v_pk_mul_f32 v[62:63], v[160:161], v[154:155] op_sel_hi:[0,1]
	v_add_f32_dpp v58, v58, v58 row_half_mirror row_mask:0xf bank_mask:0xf bound_ctrl:1
	v_add_f32_dpp v40, v245, v245 quad_perm:[2,3,0,1] row_mask:0xf bank_mask:0xf bound_ctrl:1
	v_pk_fma_f32 v[62:63], v[92:93], v[150:151], v[62:63]
	v_add_f32_dpp v58, v58, v58 row_mirror row_mask:0xf bank_mask:0xf bound_ctrl:1
	v_pk_fma_f32 v[90:91], v[156:157], v[58:59], v[60:61] op_sel_hi:[1,0,1] neg_lo:[1,0,0] neg_hi:[1,0,0]
	v_pk_fma_f32 v[92:93], v[158:159], v[58:59], v[62:63] op_sel_hi:[1,0,1] neg_lo:[1,0,0] neg_hi:[1,0,0]
	v_add_f32_dpp v41, v247, v247 quad_perm:[2,3,0,1] row_mask:0xf bank_mask:0xf bound_ctrl:1
	v_cndmask_b32_e64 v245, v40, v41, s[40:41]
	v_add_f32_dpp v40, v244, v244 quad_perm:[1,0,3,2] row_mask:0xf bank_mask:0xf bound_ctrl:1
	s_nop 0
	v_add_f32_dpp v41, v245, v245 quad_perm:[1,0,3,2] row_mask:0xf bank_mask:0xf bound_ctrl:1
	v_cndmask_b32_e64 v67, v40, v41, s[38:39]
	s_nop 0
	v_pk_mul_f32 v[64:65], v[142:143], v[92:93]
	v_pk_fma_f32 v[64:65], v[140:141], v[90:91], v[64:65]
	v_add_f32_e32 v7, v64, v65
	s_nop 1
	v_add_f32_dpp v0, v0, v0 row_mirror row_mask:0xf bank_mask:0xf bound_ctrl:1
	v_add_f32_dpp v1, v1, v1 row_mirror row_mask:0xf bank_mask:0xf bound_ctrl:1
	v_add_f32_dpp v2, v2, v2 row_mirror row_mask:0xf bank_mask:0xf bound_ctrl:1
	v_add_f32_dpp v3, v3, v3 row_mirror row_mask:0xf bank_mask:0xf bound_ctrl:1
	v_add_f32_dpp v4, v4, v4 row_mirror row_mask:0xf bank_mask:0xf bound_ctrl:1
	v_add_f32_dpp v5, v5, v5 row_mirror row_mask:0xf bank_mask:0xf bound_ctrl:1
	v_add_f32_dpp v6, v6, v6 row_mirror row_mask:0xf bank_mask:0xf bound_ctrl:1
	v_add_f32_dpp v7, v7, v7 row_mirror row_mask:0xf bank_mask:0xf bound_ctrl:1
	v_add_f32_dpp v40, v0, v0 row_half_mirror row_mask:0xf bank_mask:0xf bound_ctrl:1
	v_add_f32_dpp v41, v4, v4 row_half_mirror row_mask:0xf bank_mask:0xf bound_ctrl:1
	v_cndmask_b32_e64 v0, v40, v41, s[42:43]
	v_add_f32_dpp v40, v1, v1 row_half_mirror row_mask:0xf bank_mask:0xf bound_ctrl:1
	v_add_f32_dpp v41, v5, v5 row_half_mirror row_mask:0xf bank_mask:0xf bound_ctrl:1
	v_cndmask_b32_e64 v1, v40, v41, s[42:43]
	v_add_f32_dpp v40, v2, v2 row_half_mirror row_mask:0xf bank_mask:0xf bound_ctrl:1
	v_add_f32_dpp v41, v6, v6 row_half_mirror row_mask:0xf bank_mask:0xf bound_ctrl:1
	v_cndmask_b32_e64 v2, v40, v41, s[42:43]
	v_add_f32_dpp v40, v3, v3 row_half_mirror row_mask:0xf bank_mask:0xf bound_ctrl:1
	v_add_f32_dpp v41, v7, v7 row_half_mirror row_mask:0xf bank_mask:0xf bound_ctrl:1
	v_cndmask_b32_e64 v3, v40, v41, s[42:43]
	v_add_f32_dpp v40, v0, v0 quad_perm:[2,3,0,1] row_mask:0xf bank_mask:0xf bound_ctrl:1
	v_add_f32_dpp v41, v2, v2 quad_perm:[2,3,0,1] row_mask:0xf bank_mask:0xf bound_ctrl:1
	v_cndmask_b32_e64 v0, v40, v41, s[40:41]
	v_add_f32_dpp v40, v1, v1 quad_perm:[2,3,0,1] row_mask:0xf bank_mask:0xf bound_ctrl:1
	v_add_f32_dpp v41, v3, v3 quad_perm:[2,3,0,1] row_mask:0xf bank_mask:0xf bound_ctrl:1
	v_cndmask_b32_e64 v1, v40, v41, s[40:41]
	v_add_f32_dpp v40, v0, v0 quad_perm:[1,0,3,2] row_mask:0xf bank_mask:0xf bound_ctrl:1
	s_nop 0
	v_add_f32_dpp v41, v1, v1 quad_perm:[1,0,3,2] row_mask:0xf bank_mask:0xf bound_ctrl:1
	v_cndmask_b32_e64 v45, v40, v41, s[38:39]
	v_cndmask_b32_e64 v67, v67, v45, s[44:45]
	v_cvt_f16_f32_e32 v45, v67
	global_store_short v[242:243], v45, off
	s_add_i32 s12, s26, 16
	s_mov_b32 vcc_hi, 0x21e000
	s_cmp_eq_u32 s12, 0x100
	s_cselect_b32 vcc_lo, vcc_hi, 0xffffe000
	s_cmp_lg_u32 s36, 0
	s_cselect_b32 vcc_lo, 0x2000, vcc_lo
	s_ashr_i32 vcc_hi, vcc_lo, 31
	v_lshl_add_u64 v[242:243], v[242:243], 0, vcc
	s_add_i32 s26, s26, 16
	s_waitcnt lgkmcnt(0)
	s_barrier
; DI void scan_item(const Params& p, int item, char* smem) {
;     ...
;   auto gload = [&](int ci) {
; #pragma unroll
;     for (int i = 0; i < 3; i++) {
;       int id = tid + i * 256;
;       int st = id / 48, rem = id % 48, vec = rem >> 3, part = rem & 7;
;       int t = tof(ci * 16 + st);
;       int vi = vec < 3 ? vec : vec + 3 * dir;
;       rg_[i] = *(const u32x4*)(SIb + ((long)t * 9 + vi) * 64 + part * 8);
;     }
;   };
;     ...
;   auto ldstep = [&](const float* b) {
;     StepIn x;
;     x.r = *(const f32x4v*)(b + cg4); x.k = *(const f32x4v*)(b + 64 + cg4); x.v = b[voff];
;     x.w = *(const f32x4v*)(b + 192 + cg4); x.d = *(const f32x4v*)(b + 256 + cg4); x.b = *(const f32x4v*)(b + 320 + cg4);
;     return x;
;   };
;   for (int ci = 0; ci < nch; ci++) {
;     if (ci + 1 < nch) gload(ci + 1);
;     const float* base = sIn + (ci & 1) * 16 * 6 * 64;
;     float ykeep = 0.f;
;     StepIn cur = ldstep(base);
; #pragma unroll
;     for (int st = 0; st < 16; st++) {
;       StepIn nxt = cur;
;       if (st + 1 < 16) nxt = ldstep(base + (st + 1) * 6 * 64);
;       __builtin_amdgcn_sched_barrier(0);
;       f32x2 ra = {cur.r.x, cur.r.y}, rb = {cur.r.z, cur.r.w}, ka = {cur.k.x, cur.k.y}, kb = {cur.k.z, cur.k.w};
;       f32x2 wa = {cur.w.x, cur.w.y}, wb = {cur.w.z, cur.w.w}, da = {cur.d.x, cur.d.y}, db = {cur.d.z, cur.d.w};
;       f32x2 ba = {cur.b.x, cur.b.y}, bb2 = {cur.b.z, cur.b.w};
;       f32x2 pp = Sa * ka + Sb * kb;
;       float sa = allreduce16(pp.x + pp.y);
;       f32x2 vv2 = {cur.v, cur.v};
;       f32x2 sa2 = {sa, sa};
;       Sa = (Sa * wa + vv2 * da) - sa2 * ba;
;       Sb = (Sb * wb + vv2 * db) - sa2 * bb2;
;       f32x2 yy = Sa * ra + Sb * rb;
;       float y = allreduce16(yy.x + yy.y);
;       ykeep = (l16 == st) ? y : ykeep;
;       cur = nxt;
;     }
	ds_read_b128 v[72:75], v49 offset:24832
	ds_read_b32 v88, v50 offset:25088
	ds_read_b128 v[80:83], v49 offset:25600
	ds_read_b128 v[76:79], v49 offset:25344
	ds_read_b128 v[84:87], v49 offset:25856
	ds_read_b128 v[68:71], v49 offset:24576
	ds_read_b128 v[100:103], v49 offset:26368
	ds_read_b32 v116, v50 offset:26624
	ds_read_b128 v[108:111], v49 offset:27136
	ds_read_b128 v[104:107], v49 offset:26880
	ds_read_b128 v[112:115], v49 offset:27392
	ds_read_b128 v[96:99], v49 offset:26112
	s_add_i32 s72, s26, 32
	s_mov_b32 vcc_hi, 0x4c3800
	s_cmp_eq_u32 s72, 0x100
	s_cselect_b32 vcc_lo, vcc_hi, 0xffffb800
	s_cmp_lg_u32 s36, 0
	s_cselect_b32 vcc_lo, 0x4800, vcc_lo
	s_cmp_ge_u32 s72, 0x1100
	s_cselect_b32 vcc_lo, 0, vcc_lo
	s_ashr_i32 vcc_hi, vcc_lo, 31
	v_lshl_add_u64 v[236:237], v[236:237], 0, vcc
	v_lshl_add_u64 v[238:239], v[238:239], 0, vcc
	v_lshl_add_u64 v[240:241], v[240:241], 0, vcc
	global_load_dwordx4 v[0:3], v[236:237], off
	global_load_dwordx4 v[4:7], v[238:239], off
	global_load_dwordx4 v[8:11], v[240:241], off
	s_waitcnt lgkmcnt(6)
	ds_read_b128 v[122:125], v49 offset:27904
	ds_read_b32 v138, v50 offset:28160
	ds_read_b128 v[130:133], v49 offset:28672
	ds_read_b128 v[126:129], v49 offset:28416
	ds_read_b128 v[134:137], v49 offset:28928
	ds_read_b128 v[118:121], v49 offset:27648
	v_pk_mul_f32 v[56:57], v[90:91], v[72:73]
	v_pk_mul_f32 v[60:61], v[88:89], v[80:81] op_sel_hi:[0,1]
	v_pk_fma_f32 v[56:57], v[92:93], v[74:75], v[56:57]
	v_pk_mul_f32 v[62:63], v[88:89], v[82:83] op_sel_hi:[0,1]
	v_add_f32_e32 v58, v56, v57
	v_pk_fma_f32 v[60:61], v[90:91], v[76:77], v[60:61]
	v_pk_fma_f32 v[62:63], v[92:93], v[78:79], v[62:63]
	v_add_f32_dpp v58, v58, v58 quad_perm:[1,0,3,2] row_mask:0xf bank_mask:0xf bound_ctrl:1
	s_waitcnt vmcnt(5)
	v_cvt_f32_f16_e32 v40, v162
	v_cvt_f32_f16_sdwa v41, v162 dst_sel:DWORD dst_unused:UNUSED_PAD src0_sel:WORD_1
	v_add_f32_dpp v58, v58, v58 quad_perm:[2,3,0,1] row_mask:0xf bank_mask:0xf bound_ctrl:1
	v_cvt_f32_f16_e32 v42, v163
	v_cvt_f32_f16_sdwa v43, v163 dst_sel:DWORD dst_unused:UNUSED_PAD src0_sel:WORD_1
	v_add_f32_dpp v58, v58, v58 row_half_mirror row_mask:0xf bank_mask:0xf bound_ctrl:1
	ds_write_b128 v32, v[40:43]
	v_cvt_f32_f16_e32 v44, v164
	v_add_f32_dpp v58, v58, v58 row_mirror row_mask:0xf bank_mask:0xf bound_ctrl:1
	v_cvt_f32_f16_sdwa v45, v164 dst_sel:DWORD dst_unused:UNUSED_PAD src0_sel:WORD_1
	v_pk_fma_f32 v[90:91], v[84:85], v[58:59], v[60:61] op_sel_hi:[1,0,1] neg_lo:[1,0,0] neg_hi:[1,0,0]
	v_pk_fma_f32 v[92:93], v[86:87], v[58:59], v[62:63] op_sel_hi:[1,0,1] neg_lo:[1,0,0] neg_hi:[1,0,0]
	s_waitcnt lgkmcnt(7)
	ds_read_b128 v[144:147], v49 offset:29440
	ds_read_b32 v160, v50 offset:29696
	ds_read_b128 v[152:155], v49 offset:30208
	ds_read_b128 v[148:151], v49 offset:29952
	ds_read_b128 v[156:159], v49 offset:30464
	ds_read_b128 v[140:143], v49 offset:29184
	v_pk_mul_f32 v[56:57], v[90:91], v[100:101]
	v_pk_mul_f32 v[64:65], v[70:71], v[92:93]
	v_pk_fma_f32 v[56:57], v[92:93], v[102:103], v[56:57]
	v_pk_fma_f32 v[64:65], v[68:69], v[90:91], v[64:65]
	v_add_f32_e32 v58, v56, v57
	v_add_f32_e32 v244, v64, v65
	v_pk_mul_f32 v[60:61], v[116:117], v[108:109] op_sel_hi:[0,1]
	v_add_f32_dpp v58, v58, v58 quad_perm:[1,0,3,2] row_mask:0xf bank_mask:0xf bound_ctrl:1
	v_cvt_f32_f16_e32 v46, v165
	v_pk_fma_f32 v[60:61], v[90:91], v[104:105], v[60:61]
	v_add_f32_dpp v58, v58, v58 quad_perm:[2,3,0,1] row_mask:0xf bank_mask:0xf bound_ctrl:1
	v_cvt_f32_f16_sdwa v47, v165 dst_sel:DWORD dst_unused:UNUSED_PAD src0_sel:WORD_1
	v_pk_mul_f32 v[62:63], v[116:117], v[110:111] op_sel_hi:[0,1]
	v_add_f32_dpp v58, v58, v58 row_half_mirror row_mask:0xf bank_mask:0xf bound_ctrl:1
	ds_write_b128 v32, v[44:47] offset:16
	v_pk_fma_f32 v[62:63], v[92:93], v[106:107], v[62:63]
	v_add_f32_dpp v58, v58, v58 row_mirror row_mask:0xf bank_mask:0xf bound_ctrl:1
	v_pk_fma_f32 v[90:91], v[112:113], v[58:59], v[60:61] op_sel_hi:[1,0,1] neg_lo:[1,0,0] neg_hi:[1,0,0]
	v_pk_fma_f32 v[92:93], v[114:115], v[58:59], v[62:63] op_sel_hi:[1,0,1] neg_lo:[1,0,0] neg_hi:[1,0,0]
	s_waitcnt lgkmcnt(8)
	ds_read_b128 v[72:75], v49 offset:30976
	ds_read_b32 v88, v50 offset:31232
	ds_read_b128 v[80:83], v49 offset:31744
	ds_read_b128 v[76:79], v49 offset:31488
	ds_read_b128 v[84:87], v49 offset:32000
	ds_read_b128 v[68:71], v49 offset:30720
	v_pk_mul_f32 v[56:57], v[90:91], v[122:123]
	v_pk_mul_f32 v[64:65], v[98:99], v[92:93]
	v_pk_fma_f32 v[56:57], v[92:93], v[124:125], v[56:57]
	v_pk_fma_f32 v[64:65], v[96:97], v[90:91], v[64:65]
	v_add_f32_e32 v58, v56, v57
	v_add_f32_e32 v245, v64, v65
	v_pk_mul_f32 v[60:61], v[138:139], v[130:131] op_sel_hi:[0,1]
	v_add_f32_dpp v58, v58, v58 quad_perm:[1,0,3,2] row_mask:0xf bank_mask:0xf bound_ctrl:1
	s_waitcnt vmcnt(4)
	v_cvt_f32_f16_e32 v40, v166
	v_pk_fma_f32 v[60:61], v[90:91], v[126:127], v[60:61]
	v_add_f32_dpp v58, v58, v58 quad_perm:[2,3,0,1] row_mask:0xf bank_mask:0xf bound_ctrl:1
	v_cvt_f32_f16_sdwa v41, v166 dst_sel:DWORD dst_unused:UNUSED_PAD src0_sel:WORD_1
	v_pk_mul_f32 v[62:63], v[138:139], v[132:133] op_sel_hi:[0,1]
	v_add_f32_dpp v58, v58, v58 row_half_mirror row_mask:0xf bank_mask:0xf bound_ctrl:1
	v_cvt_f32_f16_e32 v42, v167
	v_pk_fma_f32 v[62:63], v[92:93], v[128:129], v[62:63]
	v_add_f32_dpp v58, v58, v58 row_mirror row_mask:0xf bank_mask:0xf bound_ctrl:1
	v_pk_fma_f32 v[90:91], v[134:135], v[58:59], v[60:61] op_sel_hi:[1,0,1] neg_lo:[1,0,0] neg_hi:[1,0,0]
	v_pk_fma_f32 v[92:93], v[136:137], v[58:59], v[62:63] op_sel_hi:[1,0,1] neg_lo:[1,0,0] neg_hi:[1,0,0]
	s_waitcnt lgkmcnt(7)
; DI void scan_item(const Params& p, int item, char* smem) {
;     ...
;   auto lstore = [&](int buf) {
; #pragma unroll
;     for (int i = 0; i < 3; i++) {
;       int id = tid + i * 256;
;       int st = id / 48, rem = id % 48, vec = rem >> 3, part = rem & 7;
;       h8 hv = __builtin_bit_cast(h8, rg_[i]);
;       f8 fv = __builtin_convertvector(hv, f8);
;       float* d = sIn + ((buf * 16 + st) * 6 + vec) * 64 + part * 8;
;       *(f32x4v*)d = f32x4v{fv[0], fv[1], fv[2], fv[3]};
;       *(f32x4v*)(d + 4) = f32x4v{fv[4], fv[5], fv[6], fv[7]};
;     }
;   };
;     ...
;     for (int st = 0; st < 16; st++) {
;       StepIn nxt = cur;
;       if (st + 1 < 16) nxt = ldstep(base + (st + 1) * 6 * 64);
;       __builtin_amdgcn_sched_barrier(0);
;       f32x2 ra = {cur.r.x, cur.r.y}, rb = {cur.r.z, cur.r.w}, ka = {cur.k.x, cur.k.y}, kb = {cur.k.z, cur.k.w};
;       f32x2 wa = {cur.w.x, cur.w.y}, wb = {cur.w.z, cur.w.w}, da = {cur.d.x, cur.d.y}, db = {cur.d.z, cur.d.w};
;       f32x2 ba = {cur.b.x, cur.b.y}, bb2 = {cur.b.z, cur.b.w};
;       f32x2 pp = Sa * ka + Sb * kb;
;       float sa = allreduce16(pp.x + pp.y);
;       f32x2 vv2 = {cur.v, cur.v};
;       f32x2 sa2 = {sa, sa};
;       Sa = (Sa * wa + vv2 * da) - sa2 * ba;
;       Sb = (Sb * wb + vv2 * db) - sa2 * bb2;
;       f32x2 yy = Sa * ra + Sb * rb;
;       float y = allreduce16(yy.x + yy.y);
;       ykeep = (l16 == st) ? y : ykeep;
;       cur = nxt;
;     }
	ds_read_b128 v[100:103], v49 offset:32512
	ds_read_b32 v116, v50 offset:32768
	ds_read_b128 v[108:111], v49 offset:33280
	ds_read_b128 v[104:107], v49 offset:33024
	ds_read_b128 v[112:115], v49 offset:33536
	ds_read_b128 v[96:99], v49 offset:32256
	v_pk_mul_f32 v[56:57], v[90:91], v[144:145]
	v_pk_mul_f32 v[64:65], v[120:121], v[92:93]
	v_pk_fma_f32 v[56:57], v[92:93], v[146:147], v[56:57]
	v_pk_fma_f32 v[64:65], v[118:119], v[90:91], v[64:65]
	v_add_f32_e32 v58, v56, v57
	v_add_f32_e32 v246, v64, v65
	v_pk_mul_f32 v[60:61], v[160:161], v[152:153] op_sel_hi:[0,1]
	v_add_f32_dpp v58, v58, v58 quad_perm:[1,0,3,2] row_mask:0xf bank_mask:0xf bound_ctrl:1
	v_cvt_f32_f16_sdwa v43, v167 dst_sel:DWORD dst_unused:UNUSED_PAD src0_sel:WORD_1
	v_pk_fma_f32 v[60:61], v[90:91], v[148:149], v[60:61]
	v_add_f32_dpp v58, v58, v58 quad_perm:[2,3,0,1] row_mask:0xf bank_mask:0xf bound_ctrl:1
	ds_write_b128 v33, v[40:43]
	v_pk_mul_f32 v[62:63], v[160:161], v[154:155] op_sel_hi:[0,1]
	v_add_f32_dpp v58, v58, v58 row_half_mirror row_mask:0xf bank_mask:0xf bound_ctrl:1
	v_cvt_f32_f16_e32 v44, v168
	v_pk_fma_f32 v[62:63], v[92:93], v[150:151], v[62:63]
	v_add_f32_dpp v58, v58, v58 row_mirror row_mask:0xf bank_mask:0xf bound_ctrl:1
	v_pk_fma_f32 v[90:91], v[156:157], v[58:59], v[60:61] op_sel_hi:[1,0,1] neg_lo:[1,0,0] neg_hi:[1,0,0]
	v_pk_fma_f32 v[92:93], v[158:159], v[58:59], v[62:63] op_sel_hi:[1,0,1] neg_lo:[1,0,0] neg_hi:[1,0,0]
	s_waitcnt lgkmcnt(7)
	ds_read_b128 v[122:125], v49 offset:34048
	ds_read_b32 v138, v50 offset:34304
	ds_read_b128 v[130:133], v49 offset:34816
	ds_read_b128 v[126:129], v49 offset:34560
	ds_read_b128 v[134:137], v49 offset:35072
	ds_read_b128 v[118:121], v49 offset:33792
	v_pk_mul_f32 v[56:57], v[90:91], v[72:73]
	v_pk_mul_f32 v[64:65], v[142:143], v[92:93]
	v_pk_fma_f32 v[56:57], v[92:93], v[74:75], v[56:57]
	v_pk_fma_f32 v[64:65], v[140:141], v[90:91], v[64:65]
	v_add_f32_e32 v58, v56, v57
	v_add_f32_e32 v247, v64, v65
	v_pk_mul_f32 v[60:61], v[88:89], v[80:81] op_sel_hi:[0,1]
	v_add_f32_dpp v58, v58, v58 quad_perm:[1,0,3,2] row_mask:0xf bank_mask:0xf bound_ctrl:1
	v_cvt_f32_f16_sdwa v45, v168 dst_sel:DWORD dst_unused:UNUSED_PAD src0_sel:WORD_1
	v_pk_fma_f32 v[60:61], v[90:91], v[76:77], v[60:61]
	v_add_f32_dpp v58, v58, v58 quad_perm:[2,3,0,1] row_mask:0xf bank_mask:0xf bound_ctrl:1
	v_cvt_f32_f16_e32 v46, v169
	v_pk_mul_f32 v[62:63], v[88:89], v[82:83] op_sel_hi:[0,1]
	v_add_f32_dpp v58, v58, v58 row_half_mirror row_mask:0xf bank_mask:0xf bound_ctrl:1
	v_cvt_f32_f16_sdwa v47, v169 dst_sel:DWORD dst_unused:UNUSED_PAD src0_sel:WORD_1
	v_pk_fma_f32 v[62:63], v[92:93], v[78:79], v[62:63]
	v_add_f32_dpp v58, v58, v58 row_mirror row_mask:0xf bank_mask:0xf bound_ctrl:1
	v_pk_fma_f32 v[90:91], v[84:85], v[58:59], v[60:61] op_sel_hi:[1,0,1] neg_lo:[1,0,0] neg_hi:[1,0,0]
	v_pk_fma_f32 v[92:93], v[86:87], v[58:59], v[62:63] op_sel_hi:[1,0,1] neg_lo:[1,0,0] neg_hi:[1,0,0]
	s_waitcnt lgkmcnt(7)
	ds_read_b128 v[144:147], v49 offset:35584
	ds_read_b32 v160, v50 offset:35840
	ds_read_b128 v[152:155], v49 offset:36352
	ds_read_b128 v[148:151], v49 offset:36096
	ds_read_b128 v[156:159], v49 offset:36608
	ds_read_b128 v[140:143], v49 offset:35328
	v_pk_mul_f32 v[56:57], v[90:91], v[100:101]
	v_pk_mul_f32 v[64:65], v[70:71], v[92:93]
	v_pk_fma_f32 v[56:57], v[92:93], v[102:103], v[56:57]
	v_pk_fma_f32 v[64:65], v[68:69], v[90:91], v[64:65]
	v_add_f32_e32 v58, v56, v57
	v_add_f32_e32 v248, v64, v65
	v_pk_mul_f32 v[60:61], v[116:117], v[108:109] op_sel_hi:[0,1]
	v_add_f32_dpp v58, v58, v58 quad_perm:[1,0,3,2] row_mask:0xf bank_mask:0xf bound_ctrl:1
	ds_write_b128 v33, v[44:47] offset:16
	v_pk_fma_f32 v[60:61], v[90:91], v[104:105], v[60:61]
	v_add_f32_dpp v58, v58, v58 quad_perm:[2,3,0,1] row_mask:0xf bank_mask:0xf bound_ctrl:1
	s_waitcnt vmcnt(3)
	v_cvt_f32_f16_e32 v40, v170
	v_pk_mul_f32 v[62:63], v[116:117], v[110:111] op_sel_hi:[0,1]
	v_add_f32_dpp v58, v58, v58 row_half_mirror row_mask:0xf bank_mask:0xf bound_ctrl:1
	v_cvt_f32_f16_sdwa v41, v170 dst_sel:DWORD dst_unused:UNUSED_PAD src0_sel:WORD_1
	v_pk_fma_f32 v[62:63], v[92:93], v[106:107], v[62:63]
	v_add_f32_dpp v58, v58, v58 row_mirror row_mask:0xf bank_mask:0xf bound_ctrl:1
	v_pk_fma_f32 v[90:91], v[112:113], v[58:59], v[60:61] op_sel_hi:[1,0,1] neg_lo:[1,0,0] neg_hi:[1,0,0]
	v_pk_fma_f32 v[92:93], v[114:115], v[58:59], v[62:63] op_sel_hi:[1,0,1] neg_lo:[1,0,0] neg_hi:[1,0,0]
	s_waitcnt lgkmcnt(7)
	ds_read_b128 v[72:75], v49 offset:37120
	ds_read_b32 v88, v50 offset:37376
	ds_read_b128 v[80:83], v49 offset:37888
	ds_read_b128 v[76:79], v49 offset:37632
	ds_read_b128 v[84:87], v49 offset:38144
	ds_read_b128 v[68:71], v49 offset:36864
	v_pk_mul_f32 v[56:57], v[90:91], v[122:123]
	v_pk_mul_f32 v[64:65], v[98:99], v[92:93]
	v_pk_fma_f32 v[56:57], v[92:93], v[124:125], v[56:57]
	v_pk_fma_f32 v[64:65], v[96:97], v[90:91], v[64:65]
	v_add_f32_e32 v58, v56, v57
	v_add_f32_e32 v249, v64, v65
	v_pk_mul_f32 v[60:61], v[138:139], v[130:131] op_sel_hi:[0,1]
	v_add_f32_dpp v58, v58, v58 quad_perm:[1,0,3,2] row_mask:0xf bank_mask:0xf bound_ctrl:1
	v_cvt_f32_f16_e32 v42, v171
	v_pk_fma_f32 v[60:61], v[90:91], v[126:127], v[60:61]
	v_add_f32_dpp v58, v58, v58 quad_perm:[2,3,0,1] row_mask:0xf bank_mask:0xf bound_ctrl:1
	v_cvt_f32_f16_sdwa v43, v171 dst_sel:DWORD dst_unused:UNUSED_PAD src0_sel:WORD_1
	v_pk_mul_f32 v[62:63], v[138:139], v[132:133] op_sel_hi:[0,1]
	v_add_f32_dpp v58, v58, v58 row_half_mirror row_mask:0xf bank_mask:0xf bound_ctrl:1
	ds_write_b128 v34, v[40:43]
	v_pk_fma_f32 v[62:63], v[92:93], v[128:129], v[62:63]
	v_add_f32_dpp v58, v58, v58 row_mirror row_mask:0xf bank_mask:0xf bound_ctrl:1
	v_pk_fma_f32 v[90:91], v[134:135], v[58:59], v[60:61] op_sel_hi:[1,0,1] neg_lo:[1,0,0] neg_hi:[1,0,0]
	v_pk_fma_f32 v[92:93], v[136:137], v[58:59], v[62:63] op_sel_hi:[1,0,1] neg_lo:[1,0,0] neg_hi:[1,0,0]
	s_waitcnt lgkmcnt(8)
; DI void scan_item(const Params& p, int item, char* smem) {
;     ...
;   auto lstore = [&](int buf) {
; #pragma unroll
;     for (int i = 0; i < 3; i++) {
;       int id = tid + i * 256;
;       int st = id / 48, rem = id % 48, vec = rem >> 3, part = rem & 7;
;       h8 hv = __builtin_bit_cast(h8, rg_[i]);
;       f8 fv = __builtin_convertvector(hv, f8);
;       float* d = sIn + ((buf * 16 + st) * 6 + vec) * 64 + part * 8;
;       *(f32x4v*)d = f32x4v{fv[0], fv[1], fv[2], fv[3]};
;       *(f32x4v*)(d + 4) = f32x4v{fv[4], fv[5], fv[6], fv[7]};
;     }
;   };
;     ...
;     for (int st = 0; st < 16; st++) {
;       StepIn nxt = cur;
;       if (st + 1 < 16) nxt = ldstep(base + (st + 1) * 6 * 64);
;       __builtin_amdgcn_sched_barrier(0);
;       f32x2 ra = {cur.r.x, cur.r.y}, rb = {cur.r.z, cur.r.w}, ka = {cur.k.x, cur.k.y}, kb = {cur.k.z, cur.k.w};
;       f32x2 wa = {cur.w.x, cur.w.y}, wb = {cur.w.z, cur.w.w}, da = {cur.d.x, cur.d.y}, db = {cur.d.z, cur.d.w};
;       f32x2 ba = {cur.b.x, cur.b.y}, bb2 = {cur.b.z, cur.b.w};
;       f32x2 pp = Sa * ka + Sb * kb;
;       float sa = allreduce16(pp.x + pp.y);
;       f32x2 vv2 = {cur.v, cur.v};
;       f32x2 sa2 = {sa, sa};
;       Sa = (Sa * wa + vv2 * da) - sa2 * ba;
;       Sb = (Sb * wb + vv2 * db) - sa2 * bb2;
;       f32x2 yy = Sa * ra + Sb * rb;
;       float y = allreduce16(yy.x + yy.y);
;       ykeep = (l16 == st) ? y : ykeep;
;       cur = nxt;
;     }
	ds_read_b128 v[100:103], v49 offset:38656
	ds_read_b32 v116, v50 offset:38912
	ds_read_b128 v[108:111], v49 offset:39424
	ds_read_b128 v[104:107], v49 offset:39168
	ds_read_b128 v[112:115], v49 offset:39680
	ds_read_b128 v[96:99], v49 offset:38400
	v_pk_mul_f32 v[56:57], v[90:91], v[144:145]
	v_pk_mul_f32 v[64:65], v[120:121], v[92:93]
	v_pk_fma_f32 v[56:57], v[92:93], v[146:147], v[56:57]
	v_pk_fma_f32 v[64:65], v[118:119], v[90:91], v[64:65]
	v_add_f32_e32 v58, v56, v57
	v_add_f32_e32 v250, v64, v65
	v_pk_mul_f32 v[60:61], v[160:161], v[152:153] op_sel_hi:[0,1]
	v_add_f32_dpp v58, v58, v58 quad_perm:[1,0,3,2] row_mask:0xf bank_mask:0xf bound_ctrl:1
	v_cvt_f32_f16_e32 v44, v172
	v_pk_fma_f32 v[60:61], v[90:91], v[148:149], v[60:61]
	v_add_f32_dpp v58, v58, v58 quad_perm:[2,3,0,1] row_mask:0xf bank_mask:0xf bound_ctrl:1
	v_cvt_f32_f16_sdwa v45, v172 dst_sel:DWORD dst_unused:UNUSED_PAD src0_sel:WORD_1
	v_pk_mul_f32 v[62:63], v[160:161], v[154:155] op_sel_hi:[0,1]
	v_add_f32_dpp v58, v58, v58 row_half_mirror row_mask:0xf bank_mask:0xf bound_ctrl:1
	v_cvt_f32_f16_e32 v46, v173
	v_pk_fma_f32 v[62:63], v[92:93], v[150:151], v[62:63]
	v_add_f32_dpp v58, v58, v58 row_mirror row_mask:0xf bank_mask:0xf bound_ctrl:1
	v_pk_fma_f32 v[90:91], v[156:157], v[58:59], v[60:61] op_sel_hi:[1,0,1] neg_lo:[1,0,0] neg_hi:[1,0,0]
	v_pk_fma_f32 v[92:93], v[158:159], v[58:59], v[62:63] op_sel_hi:[1,0,1] neg_lo:[1,0,0] neg_hi:[1,0,0]
	v_cvt_f32_f16_sdwa v47, v173 dst_sel:DWORD dst_unused:UNUSED_PAD src0_sel:WORD_1
	ds_write_b128 v34, v[44:47] offset:16
	s_waitcnt lgkmcnt(8)
	ds_read_b128 v[122:125], v49 offset:40192
	ds_read_b32 v138, v50 offset:40448
	ds_read_b128 v[130:133], v49 offset:40960
	ds_read_b128 v[126:129], v49 offset:40704
	ds_read_b128 v[134:137], v49 offset:41216
	ds_read_b128 v[118:121], v49 offset:39936
	v_pk_mul_f32 v[56:57], v[90:91], v[72:73]
	v_pk_mul_f32 v[64:65], v[142:143], v[92:93]
	v_pk_fma_f32 v[56:57], v[92:93], v[74:75], v[56:57]
	v_pk_fma_f32 v[64:65], v[140:141], v[90:91], v[64:65]
	v_add_f32_e32 v58, v56, v57
	v_add_f32_e32 v251, v64, v65
	v_pk_mul_f32 v[60:61], v[88:89], v[80:81] op_sel_hi:[0,1]
	v_add_f32_dpp v58, v58, v58 quad_perm:[1,0,3,2] row_mask:0xf bank_mask:0xf bound_ctrl:1
	v_add_f32_dpp v244, v244, v244 row_mirror row_mask:0xf bank_mask:0xf bound_ctrl:1
	v_pk_fma_f32 v[60:61], v[90:91], v[76:77], v[60:61]
	v_add_f32_dpp v58, v58, v58 quad_perm:[2,3,0,1] row_mask:0xf bank_mask:0xf bound_ctrl:1
	v_add_f32_dpp v245, v245, v245 row_mirror row_mask:0xf bank_mask:0xf bound_ctrl:1
	v_pk_mul_f32 v[62:63], v[88:89], v[82:83] op_sel_hi:[0,1]
	v_add_f32_dpp v58, v58, v58 row_half_mirror row_mask:0xf bank_mask:0xf bound_ctrl:1
	v_add_f32_dpp v246, v246, v246 row_mirror row_mask:0xf bank_mask:0xf bound_ctrl:1
	v_pk_fma_f32 v[62:63], v[92:93], v[78:79], v[62:63]
	v_add_f32_dpp v58, v58, v58 row_mirror row_mask:0xf bank_mask:0xf bound_ctrl:1
	v_pk_fma_f32 v[90:91], v[84:85], v[58:59], v[60:61] op_sel_hi:[1,0,1] neg_lo:[1,0,0] neg_hi:[1,0,0]
	v_pk_fma_f32 v[92:93], v[86:87], v[58:59], v[62:63] op_sel_hi:[1,0,1] neg_lo:[1,0,0] neg_hi:[1,0,0]
	s_waitcnt lgkmcnt(7)
	ds_read_b128 v[144:147], v49 offset:41728
	ds_read_b32 v160, v50 offset:41984
	ds_read_b128 v[152:155], v49 offset:42496
	ds_read_b128 v[148:151], v49 offset:42240
	ds_read_b128 v[156:159], v49 offset:42752
	ds_read_b128 v[140:143], v49 offset:41472
	v_pk_mul_f32 v[56:57], v[90:91], v[100:101]
	v_pk_mul_f32 v[64:65], v[70:71], v[92:93]
	v_pk_fma_f32 v[56:57], v[92:93], v[102:103], v[56:57]
	v_pk_fma_f32 v[64:65], v[68:69], v[90:91], v[64:65]
	v_add_f32_e32 v58, v56, v57
	v_add_f32_e32 v162, v64, v65
	v_pk_mul_f32 v[60:61], v[116:117], v[108:109] op_sel_hi:[0,1]
	v_add_f32_dpp v58, v58, v58 quad_perm:[1,0,3,2] row_mask:0xf bank_mask:0xf bound_ctrl:1
	v_add_f32_dpp v247, v247, v247 row_mirror row_mask:0xf bank_mask:0xf bound_ctrl:1
	v_pk_fma_f32 v[60:61], v[90:91], v[104:105], v[60:61]
	v_add_f32_dpp v58, v58, v58 quad_perm:[2,3,0,1] row_mask:0xf bank_mask:0xf bound_ctrl:1
	v_add_f32_dpp v248, v248, v248 row_mirror row_mask:0xf bank_mask:0xf bound_ctrl:1
	v_pk_mul_f32 v[62:63], v[116:117], v[110:111] op_sel_hi:[0,1]
	v_add_f32_dpp v58, v58, v58 row_half_mirror row_mask:0xf bank_mask:0xf bound_ctrl:1
	v_add_f32_dpp v249, v249, v249 row_mirror row_mask:0xf bank_mask:0xf bound_ctrl:1
	v_pk_fma_f32 v[62:63], v[92:93], v[106:107], v[62:63]
	v_add_f32_dpp v58, v58, v58 row_mirror row_mask:0xf bank_mask:0xf bound_ctrl:1
	v_pk_fma_f32 v[90:91], v[112:113], v[58:59], v[60:61] op_sel_hi:[1,0,1] neg_lo:[1,0,0] neg_hi:[1,0,0]
	v_pk_fma_f32 v[92:93], v[114:115], v[58:59], v[62:63] op_sel_hi:[1,0,1] neg_lo:[1,0,0] neg_hi:[1,0,0]
	s_waitcnt lgkmcnt(6)
	ds_read_b128 v[72:75], v49 offset:43264
	ds_read_b32 v88, v50 offset:43520
	ds_read_b128 v[80:83], v49 offset:44032
	ds_read_b128 v[76:79], v49 offset:43776
	ds_read_b128 v[84:87], v49 offset:44288
	ds_read_b128 v[68:71], v49 offset:43008
	v_pk_mul_f32 v[56:57], v[90:91], v[122:123]
	v_pk_mul_f32 v[64:65], v[98:99], v[92:93]
	v_pk_fma_f32 v[56:57], v[92:93], v[124:125], v[56:57]
	v_pk_fma_f32 v[64:65], v[96:97], v[90:91], v[64:65]
	v_add_f32_e32 v58, v56, v57
	v_add_f32_e32 v163, v64, v65
	v_pk_mul_f32 v[60:61], v[138:139], v[130:131] op_sel_hi:[0,1]
	v_add_f32_dpp v58, v58, v58 quad_perm:[1,0,3,2] row_mask:0xf bank_mask:0xf bound_ctrl:1
	v_add_f32_dpp v250, v250, v250 row_mirror row_mask:0xf bank_mask:0xf bound_ctrl:1
	v_pk_fma_f32 v[60:61], v[90:91], v[126:127], v[60:61]
	v_add_f32_dpp v58, v58, v58 quad_perm:[2,3,0,1] row_mask:0xf bank_mask:0xf bound_ctrl:1
	v_add_f32_dpp v251, v251, v251 row_mirror row_mask:0xf bank_mask:0xf bound_ctrl:1
	v_pk_mul_f32 v[62:63], v[138:139], v[132:133] op_sel_hi:[0,1]
	v_add_f32_dpp v58, v58, v58 row_half_mirror row_mask:0xf bank_mask:0xf bound_ctrl:1
	v_add_f32_dpp v40, v244, v244 row_half_mirror row_mask:0xf bank_mask:0xf bound_ctrl:1
	v_pk_fma_f32 v[62:63], v[92:93], v[128:129], v[62:63]
	v_add_f32_dpp v58, v58, v58 row_mirror row_mask:0xf bank_mask:0xf bound_ctrl:1
	v_pk_fma_f32 v[90:91], v[134:135], v[58:59], v[60:61] op_sel_hi:[1,0,1] neg_lo:[1,0,0] neg_hi:[1,0,0]
	v_pk_fma_f32 v[92:93], v[136:137], v[58:59], v[62:63] op_sel_hi:[1,0,1] neg_lo:[1,0,0] neg_hi:[1,0,0]
	s_waitcnt lgkmcnt(6)
; DI void scan_item(const Params& p, int item, char* smem) {
;     ...
;     for (int st = 0; st < 16; st++) {
;       StepIn nxt = cur;
;       if (st + 1 < 16) nxt = ldstep(base + (st + 1) * 6 * 64);
;       __builtin_amdgcn_sched_barrier(0);
;       f32x2 ra = {cur.r.x, cur.r.y}, rb = {cur.r.z, cur.r.w}, ka = {cur.k.x, cur.k.y}, kb = {cur.k.z, cur.k.w};
;       f32x2 wa = {cur.w.x, cur.w.y}, wb = {cur.w.z, cur.w.w}, da = {cur.d.x, cur.d.y}, db = {cur.d.z, cur.d.w};
;       f32x2 ba = {cur.b.x, cur.b.y}, bb2 = {cur.b.z, cur.b.w};
;       f32x2 pp = Sa * ka + Sb * kb;
;       float sa = allreduce16(pp.x + pp.y);
;       f32x2 vv2 = {cur.v, cur.v};
;       f32x2 sa2 = {sa, sa};
;       Sa = (Sa * wa + vv2 * da) - sa2 * ba;
;       Sb = (Sb * wb + vv2 * db) - sa2 * bb2;
;       f32x2 yy = Sa * ra + Sb * rb;
;       float y = allreduce16(yy.x + yy.y);
;       ykeep = (l16 == st) ? y : ykeep;
;       cur = nxt;
;     }
	ds_read_b128 v[100:103], v49 offset:44800
	ds_read_b32 v116, v50 offset:45056
	ds_read_b128 v[108:111], v49 offset:45568
	ds_read_b128 v[104:107], v49 offset:45312
	ds_read_b128 v[112:115], v49 offset:45824
	ds_read_b128 v[96:99], v49 offset:44544
	v_pk_mul_f32 v[56:57], v[90:91], v[144:145]
	v_pk_mul_f32 v[64:65], v[120:121], v[92:93]
	v_pk_fma_f32 v[56:57], v[92:93], v[146:147], v[56:57]
	v_pk_fma_f32 v[64:65], v[118:119], v[90:91], v[64:65]
	v_add_f32_e32 v58, v56, v57
	v_add_f32_e32 v164, v64, v65
	v_pk_mul_f32 v[60:61], v[160:161], v[152:153] op_sel_hi:[0,1]
	v_add_f32_dpp v58, v58, v58 quad_perm:[1,0,3,2] row_mask:0xf bank_mask:0xf bound_ctrl:1
	v_add_f32_dpp v41, v248, v248 row_half_mirror row_mask:0xf bank_mask:0xf bound_ctrl:1
	v_pk_fma_f32 v[60:61], v[90:91], v[148:149], v[60:61]
	v_add_f32_dpp v58, v58, v58 quad_perm:[2,3,0,1] row_mask:0xf bank_mask:0xf bound_ctrl:1
	v_cndmask_b32_e64 v244, v40, v41, s[42:43]
	v_pk_mul_f32 v[62:63], v[160:161], v[154:155] op_sel_hi:[0,1]
	v_add_f32_dpp v58, v58, v58 row_half_mirror row_mask:0xf bank_mask:0xf bound_ctrl:1
	v_add_f32_dpp v40, v245, v245 row_half_mirror row_mask:0xf bank_mask:0xf bound_ctrl:1
	v_pk_fma_f32 v[62:63], v[92:93], v[150:151], v[62:63]
	v_add_f32_dpp v58, v58, v58 row_mirror row_mask:0xf bank_mask:0xf bound_ctrl:1
	v_pk_fma_f32 v[90:91], v[156:157], v[58:59], v[60:61] op_sel_hi:[1,0,1] neg_lo:[1,0,0] neg_hi:[1,0,0]
	v_pk_fma_f32 v[92:93], v[158:159], v[58:59], v[62:63] op_sel_hi:[1,0,1] neg_lo:[1,0,0] neg_hi:[1,0,0]
	s_waitcnt lgkmcnt(6)
	ds_read_b128 v[122:125], v49 offset:46336
	ds_read_b32 v138, v50 offset:46592
	ds_read_b128 v[130:133], v49 offset:47104
	ds_read_b128 v[126:129], v49 offset:46848
	ds_read_b128 v[134:137], v49 offset:47360
	ds_read_b128 v[118:121], v49 offset:46080
	v_pk_mul_f32 v[56:57], v[90:91], v[72:73]
	v_pk_mul_f32 v[64:65], v[142:143], v[92:93]
	v_pk_fma_f32 v[56:57], v[92:93], v[74:75], v[56:57]
	v_pk_fma_f32 v[64:65], v[140:141], v[90:91], v[64:65]
	v_add_f32_e32 v58, v56, v57
	v_add_f32_e32 v165, v64, v65
	v_pk_mul_f32 v[60:61], v[88:89], v[80:81] op_sel_hi:[0,1]
	v_add_f32_dpp v58, v58, v58 quad_perm:[1,0,3,2] row_mask:0xf bank_mask:0xf bound_ctrl:1
	v_add_f32_dpp v41, v249, v249 row_half_mirror row_mask:0xf bank_mask:0xf bound_ctrl:1
	v_pk_fma_f32 v[60:61], v[90:91], v[76:77], v[60:61]
	v_add_f32_dpp v58, v58, v58 quad_perm:[2,3,0,1] row_mask:0xf bank_mask:0xf bound_ctrl:1
	v_cndmask_b32_e64 v245, v40, v41, s[42:43]
	v_pk_mul_f32 v[62:63], v[88:89], v[82:83] op_sel_hi:[0,1]
	v_add_f32_dpp v58, v58, v58 row_half_mirror row_mask:0xf bank_mask:0xf bound_ctrl:1
	v_add_f32_dpp v40, v246, v246 row_half_mirror row_mask:0xf bank_mask:0xf bound_ctrl:1
	v_pk_fma_f32 v[62:63], v[92:93], v[78:79], v[62:63]
	v_add_f32_dpp v58, v58, v58 row_mirror row_mask:0xf bank_mask:0xf bound_ctrl:1
	v_pk_fma_f32 v[90:91], v[84:85], v[58:59], v[60:61] op_sel_hi:[1,0,1] neg_lo:[1,0,0] neg_hi:[1,0,0]
	v_pk_fma_f32 v[92:93], v[86:87], v[58:59], v[62:63] op_sel_hi:[1,0,1] neg_lo:[1,0,0] neg_hi:[1,0,0]
	s_waitcnt lgkmcnt(6)
	ds_read_b128 v[144:147], v49 offset:47872
	ds_read_b32 v160, v50 offset:48128
	ds_read_b128 v[152:155], v49 offset:48640
	ds_read_b128 v[148:151], v49 offset:48384
	ds_read_b128 v[156:159], v49 offset:48896
	ds_read_b128 v[140:143], v49 offset:47616
	v_pk_mul_f32 v[56:57], v[90:91], v[100:101]
	v_pk_mul_f32 v[64:65], v[70:71], v[92:93]
	v_pk_fma_f32 v[56:57], v[92:93], v[102:103], v[56:57]
	v_pk_fma_f32 v[64:65], v[68:69], v[90:91], v[64:65]
	v_add_f32_e32 v58, v56, v57
	v_add_f32_e32 v166, v64, v65
	v_pk_mul_f32 v[60:61], v[116:117], v[108:109] op_sel_hi:[0,1]
	v_add_f32_dpp v58, v58, v58 quad_perm:[1,0,3,2] row_mask:0xf bank_mask:0xf bound_ctrl:1
	v_add_f32_dpp v41, v250, v250 row_half_mirror row_mask:0xf bank_mask:0xf bound_ctrl:1
	v_pk_fma_f32 v[60:61], v[90:91], v[104:105], v[60:61]
	v_add_f32_dpp v58, v58, v58 quad_perm:[2,3,0,1] row_mask:0xf bank_mask:0xf bound_ctrl:1
	v_cndmask_b32_e64 v246, v40, v41, s[42:43]
	v_pk_mul_f32 v[62:63], v[116:117], v[110:111] op_sel_hi:[0,1]
	v_add_f32_dpp v58, v58, v58 row_half_mirror row_mask:0xf bank_mask:0xf bound_ctrl:1
	v_add_f32_dpp v40, v247, v247 row_half_mirror row_mask:0xf bank_mask:0xf bound_ctrl:1
	v_pk_fma_f32 v[62:63], v[92:93], v[106:107], v[62:63]
	v_add_f32_dpp v58, v58, v58 row_mirror row_mask:0xf bank_mask:0xf bound_ctrl:1
	v_pk_fma_f32 v[90:91], v[112:113], v[58:59], v[60:61] op_sel_hi:[1,0,1] neg_lo:[1,0,0] neg_hi:[1,0,0]
	v_pk_fma_f32 v[92:93], v[114:115], v[58:59], v[62:63] op_sel_hi:[1,0,1] neg_lo:[1,0,0] neg_hi:[1,0,0]
	s_waitcnt lgkmcnt(6)
; DI void scan_item(const Params& p, int item, char* smem) {
;     ...
;     for (int st = 0; st < 16; st++) {
;       StepIn nxt = cur;
;       if (st + 1 < 16) nxt = ldstep(base + (st + 1) * 6 * 64);
;       __builtin_amdgcn_sched_barrier(0);
;       f32x2 ra = {cur.r.x, cur.r.y}, rb = {cur.r.z, cur.r.w}, ka = {cur.k.x, cur.k.y}, kb = {cur.k.z, cur.k.w};
;       f32x2 wa = {cur.w.x, cur.w.y}, wb = {cur.w.z, cur.w.w}, da = {cur.d.x, cur.d.y}, db = {cur.d.z, cur.d.w};
;       f32x2 ba = {cur.b.x, cur.b.y}, bb2 = {cur.b.z, cur.b.w};
;       f32x2 pp = Sa * ka + Sb * kb;
;       float sa = allreduce16(pp.x + pp.y);
;       f32x2 vv2 = {cur.v, cur.v};
;       f32x2 sa2 = {sa, sa};
;       Sa = (Sa * wa + vv2 * da) - sa2 * ba;
;       Sb = (Sb * wb + vv2 * db) - sa2 * bb2;
;       f32x2 yy = Sa * ra + Sb * rb;
;       float y = allreduce16(yy.x + yy.y);
;       ykeep = (l16 == st) ? y : ykeep;
;       cur = nxt;
;     }
;     { _Float16 yh = (_Float16)ykeep; yb[(long)tof(ci * 16 + l16) * 256 + rowl] = __builtin_bit_cast(u16, yh); }
;     if (ci + 1 < nch) lstore((ci + 1) & 1);
	v_pk_mul_f32 v[56:57], v[90:91], v[122:123]
	v_pk_mul_f32 v[64:65], v[98:99], v[92:93]
	v_pk_fma_f32 v[56:57], v[92:93], v[124:125], v[56:57]
	v_pk_fma_f32 v[64:65], v[96:97], v[90:91], v[64:65]
	v_add_f32_e32 v58, v56, v57
	v_add_f32_e32 v167, v64, v65
	v_pk_mul_f32 v[60:61], v[138:139], v[130:131] op_sel_hi:[0,1]
	v_add_f32_dpp v58, v58, v58 quad_perm:[1,0,3,2] row_mask:0xf bank_mask:0xf bound_ctrl:1
	v_add_f32_dpp v41, v251, v251 row_half_mirror row_mask:0xf bank_mask:0xf bound_ctrl:1
	v_pk_fma_f32 v[60:61], v[90:91], v[126:127], v[60:61]
	v_add_f32_dpp v58, v58, v58 quad_perm:[2,3,0,1] row_mask:0xf bank_mask:0xf bound_ctrl:1
	v_cndmask_b32_e64 v247, v40, v41, s[42:43]
	v_pk_mul_f32 v[62:63], v[138:139], v[132:133] op_sel_hi:[0,1]
	v_add_f32_dpp v58, v58, v58 row_half_mirror row_mask:0xf bank_mask:0xf bound_ctrl:1
	v_add_f32_dpp v40, v244, v244 quad_perm:[2,3,0,1] row_mask:0xf bank_mask:0xf bound_ctrl:1
	v_pk_fma_f32 v[62:63], v[92:93], v[128:129], v[62:63]
	v_add_f32_dpp v58, v58, v58 row_mirror row_mask:0xf bank_mask:0xf bound_ctrl:1
	v_pk_fma_f32 v[90:91], v[134:135], v[58:59], v[60:61] op_sel_hi:[1,0,1] neg_lo:[1,0,0] neg_hi:[1,0,0]
	v_pk_fma_f32 v[92:93], v[136:137], v[58:59], v[62:63] op_sel_hi:[1,0,1] neg_lo:[1,0,0] neg_hi:[1,0,0]
	s_waitcnt lgkmcnt(0)
	v_pk_mul_f32 v[56:57], v[90:91], v[144:145]
	v_pk_mul_f32 v[64:65], v[120:121], v[92:93]
	v_pk_fma_f32 v[56:57], v[92:93], v[146:147], v[56:57]
	v_pk_fma_f32 v[64:65], v[118:119], v[90:91], v[64:65]
	v_add_f32_e32 v58, v56, v57
	v_add_f32_e32 v168, v64, v65
	v_pk_mul_f32 v[60:61], v[160:161], v[152:153] op_sel_hi:[0,1]
	v_add_f32_dpp v58, v58, v58 quad_perm:[1,0,3,2] row_mask:0xf bank_mask:0xf bound_ctrl:1
	v_add_f32_dpp v41, v246, v246 quad_perm:[2,3,0,1] row_mask:0xf bank_mask:0xf bound_ctrl:1
	v_pk_fma_f32 v[60:61], v[90:91], v[148:149], v[60:61]
	v_add_f32_dpp v58, v58, v58 quad_perm:[2,3,0,1] row_mask:0xf bank_mask:0xf bound_ctrl:1
	v_cndmask_b32_e64 v244, v40, v41, s[40:41]
	v_pk_mul_f32 v[62:63], v[160:161], v[154:155] op_sel_hi:[0,1]
	v_add_f32_dpp v58, v58, v58 row_half_mirror row_mask:0xf bank_mask:0xf bound_ctrl:1
	v_add_f32_dpp v40, v245, v245 quad_perm:[2,3,0,1] row_mask:0xf bank_mask:0xf bound_ctrl:1
	v_pk_fma_f32 v[62:63], v[92:93], v[150:151], v[62:63]
	v_add_f32_dpp v58, v58, v58 row_mirror row_mask:0xf bank_mask:0xf bound_ctrl:1
	v_pk_fma_f32 v[90:91], v[156:157], v[58:59], v[60:61] op_sel_hi:[1,0,1] neg_lo:[1,0,0] neg_hi:[1,0,0]
	v_pk_fma_f32 v[92:93], v[158:159], v[58:59], v[62:63] op_sel_hi:[1,0,1] neg_lo:[1,0,0] neg_hi:[1,0,0]
	v_add_f32_dpp v41, v247, v247 quad_perm:[2,3,0,1] row_mask:0xf bank_mask:0xf bound_ctrl:1
	v_cndmask_b32_e64 v245, v40, v41, s[40:41]
	v_add_f32_dpp v40, v244, v244 quad_perm:[1,0,3,2] row_mask:0xf bank_mask:0xf bound_ctrl:1
	s_nop 0
	v_add_f32_dpp v41, v245, v245 quad_perm:[1,0,3,2] row_mask:0xf bank_mask:0xf bound_ctrl:1
	v_cndmask_b32_e64 v67, v40, v41, s[38:39]
	s_nop 0
	v_pk_mul_f32 v[64:65], v[142:143], v[92:93]
	v_pk_fma_f32 v[64:65], v[140:141], v[90:91], v[64:65]
	v_add_f32_e32 v169, v64, v65
	s_nop 1
	v_add_f32_dpp v162, v162, v162 row_mirror row_mask:0xf bank_mask:0xf bound_ctrl:1
	v_add_f32_dpp v163, v163, v163 row_mirror row_mask:0xf bank_mask:0xf bound_ctrl:1
	v_add_f32_dpp v164, v164, v164 row_mirror row_mask:0xf bank_mask:0xf bound_ctrl:1
	v_add_f32_dpp v165, v165, v165 row_mirror row_mask:0xf bank_mask:0xf bound_ctrl:1
	v_add_f32_dpp v166, v166, v166 row_mirror row_mask:0xf bank_mask:0xf bound_ctrl:1
	v_add_f32_dpp v167, v167, v167 row_mirror row_mask:0xf bank_mask:0xf bound_ctrl:1
	v_add_f32_dpp v168, v168, v168 row_mirror row_mask:0xf bank_mask:0xf bound_ctrl:1
	v_add_f32_dpp v169, v169, v169 row_mirror row_mask:0xf bank_mask:0xf bound_ctrl:1
	v_add_f32_dpp v40, v162, v162 row_half_mirror row_mask:0xf bank_mask:0xf bound_ctrl:1
	v_add_f32_dpp v41, v166, v166 row_half_mirror row_mask:0xf bank_mask:0xf bound_ctrl:1
	v_cndmask_b32_e64 v162, v40, v41, s[42:43]
	v_add_f32_dpp v40, v163, v163 row_half_mirror row_mask:0xf bank_mask:0xf bound_ctrl:1
	v_add_f32_dpp v41, v167, v167 row_half_mirror row_mask:0xf bank_mask:0xf bound_ctrl:1
	v_cndmask_b32_e64 v163, v40, v41, s[42:43]
	v_add_f32_dpp v40, v164, v164 row_half_mirror row_mask:0xf bank_mask:0xf bound_ctrl:1
	v_add_f32_dpp v41, v168, v168 row_half_mirror row_mask:0xf bank_mask:0xf bound_ctrl:1
	v_cndmask_b32_e64 v164, v40, v41, s[42:43]
	v_add_f32_dpp v40, v165, v165 row_half_mirror row_mask:0xf bank_mask:0xf bound_ctrl:1
	v_add_f32_dpp v41, v169, v169 row_half_mirror row_mask:0xf bank_mask:0xf bound_ctrl:1
	v_cndmask_b32_e64 v165, v40, v41, s[42:43]
	v_add_f32_dpp v40, v162, v162 quad_perm:[2,3,0,1] row_mask:0xf bank_mask:0xf bound_ctrl:1
	v_add_f32_dpp v41, v164, v164 quad_perm:[2,3,0,1] row_mask:0xf bank_mask:0xf bound_ctrl:1
	v_cndmask_b32_e64 v162, v40, v41, s[40:41]
	v_add_f32_dpp v40, v163, v163 quad_perm:[2,3,0,1] row_mask:0xf bank_mask:0xf bound_ctrl:1
	v_add_f32_dpp v41, v165, v165 quad_perm:[2,3,0,1] row_mask:0xf bank_mask:0xf bound_ctrl:1
	v_cndmask_b32_e64 v163, v40, v41, s[40:41]
	v_add_f32_dpp v40, v162, v162 quad_perm:[1,0,3,2] row_mask:0xf bank_mask:0xf bound_ctrl:1
	s_nop 0
	v_add_f32_dpp v41, v163, v163 quad_perm:[1,0,3,2] row_mask:0xf bank_mask:0xf bound_ctrl:1
	v_cndmask_b32_e64 v45, v40, v41, s[38:39]
	v_cndmask_b32_e64 v67, v67, v45, s[44:45]
	v_cvt_f16_f32_e32 v45, v67
	global_store_short v[242:243], v45, off
	s_add_i32 s12, s26, 16
	s_mov_b32 vcc_hi, 0x21e000
	s_cmp_eq_u32 s12, 0x100
	s_cselect_b32 vcc_lo, vcc_hi, 0xffffe000
	s_cmp_lg_u32 s36, 0
	s_cselect_b32 vcc_lo, 0x2000, vcc_lo
	s_ashr_i32 vcc_hi, vcc_lo, 31
	v_lshl_add_u64 v[242:243], v[242:243], 0, vcc
	s_add_i32 s26, s26, 16
	s_waitcnt lgkmcnt(0)
	s_barrier
	s_cmpk_lg_i32 s26, 0x1100
	s_cbranch_scc1 .Lscan_loop
	s_waitcnt vmcnt(0)
	s_branch .LBB0_155
